# v039 + MLA: rescale rare blocks moved out of line (common path falls through, branch not taken)
# baseline (speedup 1.0000x reference)
.LBB0_905:
	ds_read_b128 v[118:121], v181 offset:13344
	ds_read_b128 v[122:125], v181 offset:20000
	s_waitcnt lgkmcnt(3)
	v_mfma_f32_32x32x16_bf16 v[128:143], v[96:99], v[144:147], v[32:47]
	v_exp_f32_e32 v117, v80
	v_exp_f32_e32 v126, v81
	v_exp_f32_e32 v127, v82
	v_exp_f32_e32 v213, v83
	v_exp_f32_e32 v214, v84
	v_exp_f32_e32 v215, v85
	s_waitcnt lgkmcnt(2)
	v_mfma_f32_32x32x16_bf16 v[96:111], v[112:115], v[144:147], v[32:47]
	ds_read_b128 v[80:83], v181 offset:13376
	ds_read_b128 v[112:115], v181 offset:20032
	s_waitcnt lgkmcnt(3)
	v_mfma_f32_32x32x16_bf16 v[128:143], v[118:121], v[148:151], v[128:143]
	v_exp_f32_e32 v216, v86
	v_exp_f32_e32 v217, v88
	v_add_f32_e32 v88, v127, v117
	v_add_f32_e32 v86, v213, v126
	s_waitcnt lgkmcnt(2)
	v_mfma_f32_32x32x16_bf16 v[96:111], v[122:125], v[148:151], v[96:111]
	v_cvt_pk_bf16_f32 v84, v117, v126
	v_add_f32_e32 v117, v214, v88
	v_add_f32_e32 v122, v215, v86
	v_exp_f32_e32 v87, v87
	v_exp_f32_e32 v218, v89
	v_exp_f32_e32 v219, v90
	v_exp_f32_e32 v220, v91
	v_cvt_pk_bf16_f32 v85, v127, v213
	v_cvt_pk_bf16_f32 v86, v214, v215
	ds_read_b128 v[88:91], v181 offset:13408
	ds_read_b128 v[118:121], v181 offset:20064
	s_waitcnt lgkmcnt(3)
	v_mfma_f32_32x32x16_bf16 v[128:143], v[80:83], v[152:155], v[128:143]
	v_add_f32_e32 v80, v216, v117
	v_add_f32_e32 v81, v87, v122
	v_add_f32_e32 v82, v217, v80
	v_add_f32_e32 v81, v218, v81
	v_add_f32_e32 v82, v219, v82
	v_add_f32_e32 v83, v220, v81
	s_waitcnt lgkmcnt(2)
	v_mfma_f32_32x32x16_bf16 v[96:111], v[112:115], v[152:155], v[96:111]
	v_exp_f32_e32 v123, v92
	v_exp_f32_e32 v124, v93
	v_exp_f32_e32 v125, v94
	v_exp_f32_e32 v126, v95
	v_cvt_pk_bf16_f32 v87, v216, v87
	v_cvt_pk_bf16_f32 v80, v217, v218
	v_cvt_pk_bf16_f32 v81, v219, v220
	ds_read_b128 v[92:95], v181 offset:13440
	ds_read_b128 v[112:115], v181 offset:20096
	s_waitcnt lgkmcnt(3)
	v_mfma_f32_32x32x16_bf16 v[128:143], v[88:91], v[156:159], v[128:143]
	v_exp_f32_e32 v117, v64
	v_exp_f32_e32 v122, v65
	v_add_f32_e32 v64, v123, v82
	v_add_f32_e32 v65, v124, v83
	v_exp_f32_e32 v214, v68
	v_exp_f32_e32 v215, v69
	s_waitcnt lgkmcnt(2)
	v_mfma_f32_32x32x16_bf16 v[96:111], v[118:121], v[156:159], v[96:111]
	v_add_f32_e32 v68, v125, v64
	v_add_f32_e32 v69, v126, v65
	v_exp_f32_e32 v127, v66
	v_exp_f32_e32 v213, v67
	v_cvt_pk_bf16_f32 v82, v123, v124
	v_cvt_pk_bf16_f32 v83, v125, v126
	ds_read_b128 v[64:67], v181 offset:13472
	ds_read_b128 v[88:91], v181 offset:20128
	s_waitcnt lgkmcnt(3)
	v_mfma_f32_32x32x16_bf16 v[128:143], v[92:95], v[160:163], v[128:143]
	v_exp_f32_e32 v118, v70
	v_add_f32_e32 v70, v117, v68
	v_add_f32_e32 v69, v122, v69
	v_exp_f32_e32 v119, v72
	v_add_f32_e32 v70, v127, v70
	v_add_f32_e32 v72, v213, v69
	s_waitcnt lgkmcnt(2)
	v_mfma_f32_32x32x16_bf16 v[96:111], v[112:115], v[160:163], v[96:111]
	v_add_f32_e32 v112, v214, v70
	v_add_f32_e32 v113, v215, v72
	v_exp_f32_e32 v71, v71
	v_exp_f32_e32 v120, v73
	v_exp_f32_e32 v121, v74
	v_exp_f32_e32 v123, v75
	v_cvt_pk_bf16_f32 v68, v117, v122
	v_cvt_pk_bf16_f32 v69, v127, v213
	v_cvt_pk_bf16_f32 v70, v214, v215
	ds_read_b128 v[72:75], v210 offset:53248
	ds_read_b128 v[92:95], v210 offset:57856
	s_waitcnt lgkmcnt(3)
	v_mfma_f32_32x32x16_bf16 v[128:143], v[64:67], v[164:167], v[128:143]
	v_add_f32_e32 v64, v118, v112
	v_add_f32_e32 v65, v71, v113
	v_add_f32_e32 v66, v119, v64
	v_add_f32_e32 v65, v120, v65
	v_add_f32_e32 v66, v121, v66
	v_add_f32_e32 v67, v123, v65
	s_waitcnt lgkmcnt(2)
	v_mfma_f32_32x32x16_bf16 v[96:111], v[88:91], v[164:167], v[96:111]
	v_exp_f32_e32 v114, v76
	v_exp_f32_e32 v115, v77
	v_exp_f32_e32 v117, v78
	v_exp_f32_e32 v122, v79
	v_cvt_pk_bf16_f32 v71, v118, v71
	v_cvt_pk_bf16_f32 v64, v119, v120
	v_cvt_pk_bf16_f32 v65, v121, v123
	ds_read_b128 v[76:79], v210 offset:53280
	ds_read_b128 v[88:91], v210 offset:57888
	s_waitcnt lgkmcnt(3)
	v_mfma_f32_32x32x16_bf16 v[0:15], v[72:75], v[84:87], v[0:15]
	v_add_f32_e32 v72, v114, v66
	v_add_f32_e32 v67, v115, v67
	v_add_f32_e32 v112, v117, v72
	v_add_f32_e32 v113, v122, v67
	v_cvt_pk_bf16_f32 v66, v114, v115
	v_cvt_pk_bf16_f32 v67, v117, v122
	s_waitcnt lgkmcnt(2)
	v_mfma_f32_32x32x16_bf16 v[16:31], v[92:95], v[84:87], v[16:31]
	ds_read_b128 v[72:75], v210 offset:53312
	s_waitcnt lgkmcnt(2)
	v_mfma_f32_32x32x16_bf16 v[0:15], v[76:79], v[80:83], v[0:15]
	ds_read_b128 v[76:79], v210 offset:57920
	s_waitcnt lgkmcnt(2)
	v_mfma_f32_32x32x16_bf16 v[16:31], v[88:91], v[80:83], v[16:31]
	ds_read_b128 v[80:83], v210 offset:53344
	ds_read_b128 v[88:91], v210 offset:57952
	s_waitcnt lgkmcnt(3)
	v_mfma_f32_32x32x16_bf16 v[0:15], v[72:75], v[68:71], v[0:15]
	s_waitcnt lgkmcnt(2)
	v_mfma_f32_32x32x16_bf16 v[16:31], v[76:79], v[68:71], v[16:31]
	s_waitcnt lgkmcnt(1)
	v_mfma_f32_32x32x16_bf16 v[0:15], v[80:83], v[64:67], v[0:15]
	v_add_f32_e32 v221, v112, v113
	v_cmp_lt_f32_e32 vcc, s58, v221
	v_add_f32_e32 v86, v116, v221
	s_waitcnt lgkmcnt(0)
	v_mfma_f32_32x32x16_bf16 v[16:31], v[88:91], v[64:67], v[16:31]
	ds_read_b128 v[64:67], v181 offset:26624
	ds_read_b128 v[80:83], v181 offset:33280
	s_cbranch_vccnz .Lmla_rare_a_1

.LBB0_911:
	ds_read_b128 v[88:91], v181 offset:26656
	ds_read_b128 v[92:95], v181 offset:33312
	s_waitcnt lgkmcnt(3)
	v_mfma_f32_32x32x16_bf16 v[112:127], v[64:67], v[144:147], v[32:47]
	v_exp_f32_e32 v87, v128
	v_exp_f32_e32 v213, v129
	v_exp_f32_e32 v214, v130
	v_exp_f32_e32 v215, v131
	v_exp_f32_e32 v132, v132
	v_exp_f32_e32 v133, v133
	s_waitcnt lgkmcnt(2)
	v_mfma_f32_32x32x16_bf16 v[64:79], v[80:83], v[144:147], v[32:47]
	ds_read_b128 v[80:83], v181 offset:26688
	ds_read_b128 v[128:131], v181 offset:33344
	s_waitcnt lgkmcnt(3)
	v_mfma_f32_32x32x16_bf16 v[112:127], v[88:91], v[148:151], v[112:127]
	v_cvt_pk_bf16_f32 v88, v87, v213
	v_add_f32_e32 v87, v214, v87
	v_add_f32_e32 v90, v215, v213
	v_add_f32_e32 v87, v132, v87
	s_waitcnt lgkmcnt(2)
	v_mfma_f32_32x32x16_bf16 v[64:79], v[92:95], v[148:151], v[64:79]
	v_add_f32_e32 v91, v133, v90
	v_exp_f32_e32 v216, v134
	v_exp_f32_e32 v217, v135
	v_exp_f32_e32 v136, v136
	v_exp_f32_e32 v137, v137
	v_exp_f32_e32 v138, v138
	v_exp_f32_e32 v139, v139
	v_cvt_pk_bf16_f32 v89, v214, v215
	v_cvt_pk_bf16_f32 v90, v132, v133
	ds_read_b128 v[92:95], v181 offset:26720
	ds_read_b128 v[132:135], v181 offset:33376
	s_waitcnt lgkmcnt(3)
	v_mfma_f32_32x32x16_bf16 v[112:127], v[80:83], v[152:155], v[112:127]
	v_add_f32_e32 v80, v216, v87
	v_add_f32_e32 v81, v217, v91
	v_add_f32_e32 v82, v136, v80
	v_add_f32_e32 v81, v137, v81
	v_add_f32_e32 v82, v138, v82
	v_add_f32_e32 v83, v139, v81
	s_waitcnt lgkmcnt(2)
	v_mfma_f32_32x32x16_bf16 v[64:79], v[128:131], v[152:155], v[64:79]
	v_exp_f32_e32 v140, v140
	v_exp_f32_e32 v141, v141
	v_exp_f32_e32 v142, v142
	v_exp_f32_e32 v143, v143
	v_cvt_pk_bf16_f32 v91, v216, v217
	v_cvt_pk_bf16_f32 v80, v136, v137
	v_cvt_pk_bf16_f32 v81, v138, v139
	ds_read_b128 v[128:131], v181 offset:26752
	ds_read_b128 v[136:139], v181 offset:33408
	s_waitcnt lgkmcnt(3)
	v_mfma_f32_32x32x16_bf16 v[112:127], v[92:95], v[156:159], v[112:127]
	v_exp_f32_e32 v87, v96
	v_add_f32_e32 v92, v140, v82
	v_add_f32_e32 v83, v141, v83
	v_exp_f32_e32 v216, v100
	v_exp_f32_e32 v217, v101
	v_add_f32_e32 v100, v142, v92
	s_waitcnt lgkmcnt(2)
	v_mfma_f32_32x32x16_bf16 v[64:79], v[132:135], v[156:159], v[64:79]
	v_add_f32_e32 v101, v143, v83
	v_exp_f32_e32 v213, v97
	v_exp_f32_e32 v214, v98
	v_exp_f32_e32 v215, v99
	v_cvt_pk_bf16_f32 v82, v140, v141
	v_cvt_pk_bf16_f32 v83, v142, v143
	ds_read_b128 v[92:95], v181 offset:26784
	ds_read_b128 v[96:99], v181 offset:33440
	s_waitcnt lgkmcnt(3)
	v_mfma_f32_32x32x16_bf16 v[112:127], v[128:131], v[160:163], v[112:127]
	v_exp_f32_e32 v132, v102
	v_add_f32_e32 v102, v87, v100
	v_add_f32_e32 v101, v213, v101
	v_cvt_pk_bf16_f32 v100, v87, v213
	v_add_f32_e32 v87, v214, v102
	v_add_f32_e32 v102, v215, v101
	s_waitcnt lgkmcnt(2)
	v_mfma_f32_32x32x16_bf16 v[64:79], v[136:139], v[160:163], v[64:79]
	v_add_f32_e32 v87, v216, v87
	v_add_f32_e32 v136, v217, v102
	v_exp_f32_e32 v103, v103
	v_exp_f32_e32 v133, v104
	v_exp_f32_e32 v134, v105
	v_exp_f32_e32 v135, v106
	v_exp_f32_e32 v140, v107
	v_cvt_pk_bf16_f32 v101, v214, v215
	v_cvt_pk_bf16_f32 v102, v216, v217
	ds_read_b128 v[104:107], v210 offset:62464
	ds_read_b128 v[128:131], v211 offset:13824
	s_waitcnt lgkmcnt(3)
	v_mfma_f32_32x32x16_bf16 v[112:127], v[92:95], v[164:167], v[112:127]
	v_add_f32_e32 v87, v132, v87
	v_add_f32_e32 v92, v103, v136
	v_add_f32_e32 v87, v133, v87
	v_add_f32_e32 v93, v134, v92
	v_add_f32_e32 v87, v135, v87
	v_add_f32_e32 v94, v140, v93
	s_waitcnt lgkmcnt(2)
	v_mfma_f32_32x32x16_bf16 v[64:79], v[96:99], v[164:167], v[64:79]
	v_exp_f32_e32 v137, v108
	v_exp_f32_e32 v138, v109
	v_exp_f32_e32 v139, v110
	v_exp_f32_e32 v141, v111
	v_cvt_pk_bf16_f32 v103, v132, v103
	v_cvt_pk_bf16_f32 v92, v133, v134
	v_cvt_pk_bf16_f32 v93, v135, v140
	ds_read_b128 v[96:99], v210 offset:62496
	ds_read_b128 v[108:111], v211 offset:13856
	s_waitcnt lgkmcnt(3)
	v_mfma_f32_32x32x16_bf16 v[0:15], v[104:107], v[88:91], v[0:15]
	v_add_f32_e32 v87, v137, v87
	v_add_f32_e32 v95, v138, v94
	v_add_f32_e32 v132, v139, v87
	v_add_f32_e32 v133, v141, v95
	v_cvt_pk_bf16_f32 v94, v137, v138
	v_cvt_pk_bf16_f32 v95, v139, v141
	s_waitcnt lgkmcnt(2)
	v_mfma_f32_32x32x16_bf16 v[16:31], v[128:131], v[88:91], v[16:31]
	ds_read_b128 v[88:91], v210 offset:62528
	s_waitcnt lgkmcnt(2)
	v_mfma_f32_32x32x16_bf16 v[0:15], v[96:99], v[80:83], v[0:15]
	ds_read_b128 v[96:99], v211 offset:13888
	s_waitcnt lgkmcnt(2)
	v_mfma_f32_32x32x16_bf16 v[16:31], v[108:111], v[80:83], v[16:31]
	ds_read_b128 v[80:83], v210 offset:62560
	ds_read_b128 v[104:107], v211 offset:13920
	s_waitcnt lgkmcnt(3)
	v_mfma_f32_32x32x16_bf16 v[0:15], v[88:91], v[100:103], v[0:15]
	s_waitcnt lgkmcnt(2)
	v_mfma_f32_32x32x16_bf16 v[16:31], v[96:99], v[100:103], v[16:31]
	s_waitcnt lgkmcnt(1)
	v_mfma_f32_32x32x16_bf16 v[0:15], v[80:83], v[92:95], v[0:15]
	v_add_f32_e32 v221, v132, v133
	v_cmp_lt_f32_e32 vcc, s58, v221
	v_add_f32_e32 v102, v86, v221
	s_waitcnt lgkmcnt(0)
	v_mfma_f32_32x32x16_bf16 v[16:31], v[104:107], v[92:95], v[16:31]
	s_waitcnt vmcnt(0)
	s_barrier
	ds_read_b128 v[80:83], v181 offset:39936
	ds_read_b128 v[96:99], v181 offset:46592
	s_cbranch_vccnz .Lmla_rare_a_2

.LBB0_917:
	ds_read_b128 v[104:107], v181 offset:39968
	ds_read_b128 v[108:111], v181 offset:46624
	s_waitcnt lgkmcnt(3)
	v_mfma_f32_32x32x16_bf16 v[128:143], v[80:83], v[144:147], v[32:47]
	v_exp_f32_e32 v103, v112
	v_exp_f32_e32 v213, v113
	v_exp_f32_e32 v214, v114
	v_exp_f32_e32 v215, v115
	v_exp_f32_e32 v116, v116
	v_exp_f32_e32 v117, v117
	s_waitcnt lgkmcnt(2)
	v_mfma_f32_32x32x16_bf16 v[80:95], v[96:99], v[144:147], v[32:47]
	ds_read_b128 v[96:99], v181 offset:40000
	ds_read_b128 v[112:115], v181 offset:46656
	s_waitcnt lgkmcnt(3)
	v_mfma_f32_32x32x16_bf16 v[128:143], v[104:107], v[148:151], v[128:143]
	v_cvt_pk_bf16_f32 v104, v103, v213
	v_add_f32_e32 v103, v214, v103
	v_add_f32_e32 v106, v215, v213
	v_add_f32_e32 v103, v116, v103
	s_waitcnt lgkmcnt(2)
	v_mfma_f32_32x32x16_bf16 v[80:95], v[108:111], v[148:151], v[80:95]
	v_add_f32_e32 v107, v117, v106
	v_exp_f32_e32 v216, v118
	v_exp_f32_e32 v217, v119
	v_exp_f32_e32 v120, v120
	v_exp_f32_e32 v121, v121
	v_exp_f32_e32 v122, v122
	v_exp_f32_e32 v123, v123
	v_cvt_pk_bf16_f32 v105, v214, v215
	v_cvt_pk_bf16_f32 v106, v116, v117
	ds_read_b128 v[108:111], v181 offset:40032
	ds_read_b128 v[116:119], v181 offset:46688
	s_waitcnt lgkmcnt(3)
	v_mfma_f32_32x32x16_bf16 v[128:143], v[96:99], v[152:155], v[128:143]
	v_add_f32_e32 v96, v216, v103
	v_add_f32_e32 v97, v217, v107
	v_add_f32_e32 v98, v120, v96
	v_add_f32_e32 v97, v121, v97
	v_add_f32_e32 v98, v122, v98
	v_add_f32_e32 v99, v123, v97
	s_waitcnt lgkmcnt(2)
	v_mfma_f32_32x32x16_bf16 v[80:95], v[112:115], v[152:155], v[80:95]
	v_exp_f32_e32 v124, v124
	v_exp_f32_e32 v125, v125
	v_exp_f32_e32 v126, v126
	v_exp_f32_e32 v127, v127
	v_cvt_pk_bf16_f32 v107, v216, v217
	v_cvt_pk_bf16_f32 v96, v120, v121
	v_cvt_pk_bf16_f32 v97, v122, v123
	ds_read_b128 v[112:115], v181 offset:40064
	ds_read_b128 v[120:123], v181 offset:46720
	s_waitcnt lgkmcnt(3)
	v_mfma_f32_32x32x16_bf16 v[128:143], v[108:111], v[156:159], v[128:143]
	v_exp_f32_e32 v103, v64
	v_exp_f32_e32 v213, v65
	v_add_f32_e32 v64, v124, v98
	v_add_f32_e32 v65, v125, v99
	v_exp_f32_e32 v216, v68
	v_exp_f32_e32 v217, v69
	s_waitcnt lgkmcnt(2)
	v_mfma_f32_32x32x16_bf16 v[80:95], v[116:119], v[156:159], v[80:95]
	v_add_f32_e32 v68, v126, v64
	v_add_f32_e32 v69, v127, v65
	v_exp_f32_e32 v214, v66
	v_exp_f32_e32 v215, v67
	v_cvt_pk_bf16_f32 v98, v124, v125
	v_cvt_pk_bf16_f32 v99, v126, v127
	ds_read_b128 v[64:67], v181 offset:40096
	ds_read_b128 v[108:111], v181 offset:46752
	s_waitcnt lgkmcnt(3)
	v_mfma_f32_32x32x16_bf16 v[128:143], v[112:115], v[160:163], v[128:143]
	v_exp_f32_e32 v118, v73
	v_exp_f32_e32 v116, v70
	v_add_f32_e32 v70, v103, v68
	v_add_f32_e32 v69, v213, v69
	v_exp_f32_e32 v117, v72
	v_add_f32_e32 v70, v214, v70
	s_waitcnt lgkmcnt(2)
	v_mfma_f32_32x32x16_bf16 v[80:95], v[120:123], v[160:163], v[80:95]
	v_add_f32_e32 v72, v215, v69
	v_cvt_pk_bf16_f32 v68, v103, v213
	v_add_f32_e32 v103, v216, v70
	v_add_f32_e32 v120, v217, v72
	v_exp_f32_e32 v71, v71
	v_exp_f32_e32 v119, v74
	v_exp_f32_e32 v124, v75
	v_cvt_pk_bf16_f32 v69, v214, v215
	v_cvt_pk_bf16_f32 v70, v216, v217
	ds_read_b128 v[72:75], v211 offset:18432
	ds_read_b128 v[112:115], v211 offset:23040
	s_waitcnt lgkmcnt(3)
	v_mfma_f32_32x32x16_bf16 v[128:143], v[64:67], v[164:167], v[128:143]
	v_add_f32_e32 v64, v116, v103
	v_add_f32_e32 v65, v71, v120
	v_add_f32_e32 v66, v117, v64
	v_add_f32_e32 v65, v118, v65
	v_add_f32_e32 v66, v119, v66
	v_add_f32_e32 v67, v124, v65
	s_waitcnt lgkmcnt(2)
	v_mfma_f32_32x32x16_bf16 v[80:95], v[108:111], v[164:167], v[80:95]
	v_exp_f32_e32 v121, v76
	v_exp_f32_e32 v122, v77
	v_exp_f32_e32 v123, v78
	v_exp_f32_e32 v125, v79
	v_cvt_pk_bf16_f32 v71, v116, v71
	v_cvt_pk_bf16_f32 v64, v117, v118
	v_cvt_pk_bf16_f32 v65, v119, v124
	ds_read_b128 v[76:79], v211 offset:18464
	ds_read_b128 v[108:111], v211 offset:23072
	s_waitcnt lgkmcnt(3)
	v_mfma_f32_32x32x16_bf16 v[0:15], v[72:75], v[104:107], v[0:15]
	v_add_f32_e32 v72, v121, v66
	v_add_f32_e32 v67, v122, v67
	v_add_f32_e32 v103, v123, v72
	v_add_f32_e32 v116, v125, v67
	v_cvt_pk_bf16_f32 v66, v121, v122
	v_cvt_pk_bf16_f32 v67, v123, v125
	s_waitcnt lgkmcnt(2)
	v_mfma_f32_32x32x16_bf16 v[16:31], v[112:115], v[104:107], v[16:31]
	ds_read_b128 v[72:75], v211 offset:18496
	s_waitcnt lgkmcnt(2)
	v_mfma_f32_32x32x16_bf16 v[0:15], v[76:79], v[96:99], v[0:15]
	ds_read_b128 v[76:79], v211 offset:23104
	s_waitcnt lgkmcnt(2)
	v_mfma_f32_32x32x16_bf16 v[16:31], v[108:111], v[96:99], v[16:31]
	ds_read_b128 v[96:99], v211 offset:18528
	ds_read_b128 v[104:107], v211 offset:23136
	s_waitcnt lgkmcnt(3)
	v_mfma_f32_32x32x16_bf16 v[0:15], v[72:75], v[68:71], v[0:15]
	s_waitcnt lgkmcnt(2)
	v_mfma_f32_32x32x16_bf16 v[16:31], v[76:79], v[68:71], v[16:31]
	s_waitcnt lgkmcnt(1)
	v_mfma_f32_32x32x16_bf16 v[0:15], v[96:99], v[64:67], v[0:15]
	v_add_f32_e32 v221, v103, v116
	v_cmp_lt_f32_e32 vcc, s58, v221
	v_add_f32_e32 v118, v102, v221
	s_waitcnt lgkmcnt(0)
	v_mfma_f32_32x32x16_bf16 v[16:31], v[104:107], v[64:67], v[16:31]
	ds_read_b128 v[64:67], v181
	ds_read_b128 v[112:115], v181 offset:6656
	s_cbranch_vccnz .Lmla_rare_a_3

.LBB0_923:
	ds_read_b128 v[120:123], v181 offset:32
	ds_read_b128 v[124:127], v181 offset:6688
	s_waitcnt lgkmcnt(3)
	v_mfma_f32_32x32x16_bf16 v[96:111], v[64:67], v[144:147], v[32:47]
	v_exp_f32_e32 v119, v128
	v_exp_f32_e32 v213, v129
	v_exp_f32_e32 v214, v130
	v_exp_f32_e32 v215, v131
	v_exp_f32_e32 v132, v132
	v_exp_f32_e32 v133, v133
	s_waitcnt lgkmcnt(2)
	v_mfma_f32_32x32x16_bf16 v[64:79], v[112:115], v[144:147], v[32:47]
	ds_read_b128 v[112:115], v181 offset:64
	ds_read_b128 v[128:131], v181 offset:6720
	s_waitcnt lgkmcnt(3)
	v_mfma_f32_32x32x16_bf16 v[96:111], v[120:123], v[148:151], v[96:111]
	v_cvt_pk_bf16_f32 v120, v119, v213
	v_add_f32_e32 v119, v214, v119
	v_add_f32_e32 v122, v215, v213
	v_add_f32_e32 v119, v132, v119
	s_waitcnt lgkmcnt(2)
	v_mfma_f32_32x32x16_bf16 v[64:79], v[124:127], v[148:151], v[64:79]
	v_add_f32_e32 v123, v133, v122
	v_exp_f32_e32 v216, v134
	v_exp_f32_e32 v217, v135
	v_exp_f32_e32 v136, v136
	v_exp_f32_e32 v137, v137
	v_exp_f32_e32 v138, v138
	v_exp_f32_e32 v139, v139
	v_cvt_pk_bf16_f32 v121, v214, v215
	v_cvt_pk_bf16_f32 v122, v132, v133
	ds_read_b128 v[124:127], v181 offset:96
	ds_read_b128 v[132:135], v181 offset:6752
	s_waitcnt lgkmcnt(3)
	v_mfma_f32_32x32x16_bf16 v[96:111], v[112:115], v[152:155], v[96:111]
	v_add_f32_e32 v112, v216, v119
	v_add_f32_e32 v113, v217, v123
	v_add_f32_e32 v114, v136, v112
	v_add_f32_e32 v113, v137, v113
	v_add_f32_e32 v114, v138, v114
	v_add_f32_e32 v115, v139, v113
	s_waitcnt lgkmcnt(2)
	v_mfma_f32_32x32x16_bf16 v[64:79], v[128:131], v[152:155], v[64:79]
	v_exp_f32_e32 v140, v140
	v_exp_f32_e32 v141, v141
	v_exp_f32_e32 v142, v142
	v_exp_f32_e32 v143, v143
	v_cvt_pk_bf16_f32 v123, v216, v217
	v_cvt_pk_bf16_f32 v112, v136, v137
	v_cvt_pk_bf16_f32 v113, v138, v139
	ds_read_b128 v[128:131], v181 offset:128
	ds_read_b128 v[136:139], v181 offset:6784
	s_waitcnt lgkmcnt(3)
	v_mfma_f32_32x32x16_bf16 v[96:111], v[124:127], v[156:159], v[96:111]
	v_exp_f32_e32 v119, v80
	v_exp_f32_e32 v213, v81
	v_add_f32_e32 v80, v140, v114
	v_add_f32_e32 v81, v141, v115
	v_exp_f32_e32 v216, v84
	v_exp_f32_e32 v217, v85
	s_waitcnt lgkmcnt(2)
	v_mfma_f32_32x32x16_bf16 v[64:79], v[132:135], v[156:159], v[64:79]
	v_add_f32_e32 v84, v142, v80
	v_add_f32_e32 v85, v143, v81
	v_exp_f32_e32 v214, v82
	v_exp_f32_e32 v215, v83
	v_cvt_pk_bf16_f32 v114, v140, v141
	v_cvt_pk_bf16_f32 v115, v142, v143
	ds_read_b128 v[80:83], v181 offset:160
	ds_read_b128 v[124:127], v181 offset:6816
	s_waitcnt lgkmcnt(3)
	v_mfma_f32_32x32x16_bf16 v[96:111], v[128:131], v[160:163], v[96:111]
	v_exp_f32_e32 v132, v86
	v_add_f32_e32 v86, v119, v84
	v_add_f32_e32 v85, v213, v85
	v_exp_f32_e32 v133, v88
	v_add_f32_e32 v86, v214, v86
	v_add_f32_e32 v88, v215, v85
	s_waitcnt lgkmcnt(2)
	v_mfma_f32_32x32x16_bf16 v[64:79], v[136:139], v[160:163], v[64:79]
	v_cvt_pk_bf16_f32 v84, v119, v213
	v_add_f32_e32 v119, v216, v86
	v_add_f32_e32 v136, v217, v88
	v_exp_f32_e32 v87, v87
	v_exp_f32_e32 v134, v89
	v_exp_f32_e32 v135, v90
	v_exp_f32_e32 v140, v91
	v_cvt_pk_bf16_f32 v85, v214, v215
	v_cvt_pk_bf16_f32 v86, v216, v217
	ds_read_b128 v[88:91], v211 offset:27648
	ds_read_b128 v[128:131], v211 offset:32256
	s_waitcnt lgkmcnt(3)
	v_mfma_f32_32x32x16_bf16 v[96:111], v[80:83], v[164:167], v[96:111]
	v_add_f32_e32 v80, v132, v119
	v_add_f32_e32 v81, v87, v136
	v_add_f32_e32 v82, v133, v80
	v_add_f32_e32 v81, v134, v81
	v_add_f32_e32 v82, v135, v82
	v_add_f32_e32 v83, v140, v81
	s_waitcnt lgkmcnt(2)
	v_mfma_f32_32x32x16_bf16 v[64:79], v[124:127], v[164:167], v[64:79]
	v_exp_f32_e32 v137, v92
	v_exp_f32_e32 v138, v93
	v_exp_f32_e32 v139, v94
	v_exp_f32_e32 v141, v95
	v_cvt_pk_bf16_f32 v87, v132, v87
	v_cvt_pk_bf16_f32 v80, v133, v134
	v_cvt_pk_bf16_f32 v81, v135, v140
	ds_read_b128 v[92:95], v211 offset:27680
	ds_read_b128 v[124:127], v211 offset:32288
	s_waitcnt lgkmcnt(3)
	v_mfma_f32_32x32x16_bf16 v[0:15], v[88:91], v[120:123], v[0:15]
	v_add_f32_e32 v88, v137, v82
	v_add_f32_e32 v83, v138, v83
	v_add_f32_e32 v119, v139, v88
	v_add_f32_e32 v132, v141, v83
	v_cvt_pk_bf16_f32 v82, v137, v138
	v_cvt_pk_bf16_f32 v83, v139, v141
	s_waitcnt lgkmcnt(2)
	v_mfma_f32_32x32x16_bf16 v[16:31], v[128:131], v[120:123], v[16:31]
	ds_read_b128 v[88:91], v211 offset:27712
	s_waitcnt lgkmcnt(2)
	v_mfma_f32_32x32x16_bf16 v[0:15], v[92:95], v[112:115], v[0:15]
	ds_read_b128 v[92:95], v211 offset:32320
	s_waitcnt lgkmcnt(2)
	v_mfma_f32_32x32x16_bf16 v[16:31], v[124:127], v[112:115], v[16:31]
	ds_read_b128 v[112:115], v211 offset:27744
	ds_read_b128 v[120:123], v211 offset:32352
	s_waitcnt lgkmcnt(3)
	v_mfma_f32_32x32x16_bf16 v[0:15], v[88:91], v[84:87], v[0:15]
	s_waitcnt lgkmcnt(2)
	v_mfma_f32_32x32x16_bf16 v[16:31], v[92:95], v[84:87], v[16:31]
	s_waitcnt lgkmcnt(1)
	v_mfma_f32_32x32x16_bf16 v[0:15], v[112:115], v[80:83], v[0:15]
	v_add_f32_e32 v221, v119, v132
	v_cmp_lt_f32_e32 vcc, s58, v221
	v_add_f32_e32 v118, v118, v221
	s_waitcnt lgkmcnt(0)
	v_mfma_f32_32x32x16_bf16 v[16:31], v[120:123], v[80:83], v[16:31]
	s_waitcnt vmcnt(0)
	s_barrier
	ds_read_b128 v[80:83], v181 offset:13312
	ds_read_b128 v[112:115], v181 offset:19968
	s_cbranch_vccnz .Lmla_rare_a_4

.LBB0_929:
	ds_read_b128 v[138:141], v181 offset:13344
	ds_read_b128 v[214:217], v181 offset:20000
	s_waitcnt lgkmcnt(3)
	v_mfma_f32_32x32x16_bf16 v[122:137], v[80:83], v[144:147], v[32:47]
	v_exp_f32_e32 v116, v96
	v_exp_f32_e32 v117, v97
	v_exp_f32_e32 v119, v98
	v_exp_f32_e32 v120, v99
	v_exp_f32_e32 v121, v100
	v_exp_f32_e32 v142, v101
	s_waitcnt lgkmcnt(2)
	v_mfma_f32_32x32x16_bf16 v[80:95], v[112:115], v[144:147], v[32:47]
	ds_read_b128 v[96:99], v181 offset:13376
	ds_read_b128 v[112:115], v181 offset:20032
	s_waitcnt lgkmcnt(3)
	v_mfma_f32_32x32x16_bf16 v[122:137], v[138:141], v[148:151], v[122:137]
	v_exp_f32_e32 v143, v102
	v_exp_f32_e32 v213, v104
	v_add_f32_e32 v104, v119, v116
	v_add_f32_e32 v102, v120, v117
	s_waitcnt lgkmcnt(2)
	v_mfma_f32_32x32x16_bf16 v[80:95], v[214:217], v[148:151], v[80:95]
	v_cvt_pk_bf16_f32 v100, v116, v117
	v_add_f32_e32 v116, v121, v104
	v_add_f32_e32 v117, v142, v102
	v_exp_f32_e32 v103, v103
	v_exp_f32_e32 v218, v105
	v_exp_f32_e32 v219, v106
	v_exp_f32_e32 v220, v107
	v_cvt_pk_bf16_f32 v101, v119, v120
	v_cvt_pk_bf16_f32 v102, v121, v142
	ds_read_b128 v[104:107], v181 offset:13408
	ds_read_b128 v[138:141], v181 offset:20064
	s_waitcnt lgkmcnt(3)
	v_mfma_f32_32x32x16_bf16 v[122:137], v[96:99], v[152:155], v[122:137]
	v_add_f32_e32 v96, v143, v116
	v_add_f32_e32 v97, v103, v117
	v_add_f32_e32 v98, v213, v96
	v_add_f32_e32 v97, v218, v97
	v_add_f32_e32 v98, v219, v98
	v_add_f32_e32 v99, v220, v97
	s_waitcnt lgkmcnt(2)
	v_mfma_f32_32x32x16_bf16 v[80:95], v[112:115], v[152:155], v[80:95]
	v_exp_f32_e32 v119, v108
	v_exp_f32_e32 v120, v109
	v_exp_f32_e32 v121, v110
	v_exp_f32_e32 v142, v111
	v_cvt_pk_bf16_f32 v103, v143, v103
	v_cvt_pk_bf16_f32 v96, v213, v218
	v_cvt_pk_bf16_f32 v97, v219, v220
	ds_read_b128 v[108:111], v181 offset:13440
	ds_read_b128 v[112:115], v181 offset:20096
	s_waitcnt lgkmcnt(3)
	v_mfma_f32_32x32x16_bf16 v[122:137], v[104:107], v[156:159], v[122:137]
	v_exp_f32_e32 v116, v64
	v_exp_f32_e32 v117, v65
	v_add_f32_e32 v64, v119, v98
	v_add_f32_e32 v65, v120, v99
	v_exp_f32_e32 v214, v68
	v_exp_f32_e32 v215, v69
	s_waitcnt lgkmcnt(2)
	v_mfma_f32_32x32x16_bf16 v[80:95], v[138:141], v[156:159], v[80:95]
	v_add_f32_e32 v68, v121, v64
	v_add_f32_e32 v69, v142, v65
	v_exp_f32_e32 v143, v66
	v_exp_f32_e32 v213, v67
	v_cvt_pk_bf16_f32 v98, v119, v120
	v_cvt_pk_bf16_f32 v99, v121, v142
	ds_read_b128 v[64:67], v181 offset:13472
	ds_read_b128 v[104:107], v181 offset:20128
	s_waitcnt lgkmcnt(3)
	v_mfma_f32_32x32x16_bf16 v[122:137], v[108:111], v[160:163], v[122:137]
	v_exp_f32_e32 v119, v70
	v_add_f32_e32 v70, v116, v68
	v_add_f32_e32 v69, v117, v69
	v_exp_f32_e32 v120, v72
	v_add_f32_e32 v70, v143, v70
	v_add_f32_e32 v72, v213, v69
	s_waitcnt lgkmcnt(2)
	v_mfma_f32_32x32x16_bf16 v[80:95], v[112:115], v[160:163], v[80:95]
	v_add_f32_e32 v112, v214, v70
	v_add_f32_e32 v113, v215, v72
	v_exp_f32_e32 v71, v71
	v_exp_f32_e32 v121, v73
	v_exp_f32_e32 v138, v74
	v_exp_f32_e32 v139, v75
	v_cvt_pk_bf16_f32 v68, v116, v117
	v_cvt_pk_bf16_f32 v69, v143, v213
	v_cvt_pk_bf16_f32 v70, v214, v215
	ds_read_b128 v[72:75], v210 offset:53248
	ds_read_b128 v[108:111], v210 offset:57856
	s_waitcnt lgkmcnt(3)
	v_mfma_f32_32x32x16_bf16 v[122:137], v[64:67], v[164:167], v[122:137]
	v_add_f32_e32 v64, v119, v112
	v_add_f32_e32 v65, v71, v113
	v_add_f32_e32 v66, v120, v64
	v_add_f32_e32 v65, v121, v65
	v_add_f32_e32 v66, v138, v66
	v_add_f32_e32 v67, v139, v65
	s_waitcnt lgkmcnt(2)
	v_mfma_f32_32x32x16_bf16 v[80:95], v[104:107], v[164:167], v[80:95]
	v_exp_f32_e32 v114, v76
	v_exp_f32_e32 v115, v77
	v_exp_f32_e32 v116, v78
	v_exp_f32_e32 v117, v79
	v_cvt_pk_bf16_f32 v71, v119, v71
	v_cvt_pk_bf16_f32 v64, v120, v121
	v_cvt_pk_bf16_f32 v65, v138, v139
	ds_read_b128 v[76:79], v210 offset:53280
	ds_read_b128 v[104:107], v210 offset:57888
	s_waitcnt lgkmcnt(3)
	v_mfma_f32_32x32x16_bf16 v[0:15], v[72:75], v[100:103], v[0:15]
	v_add_f32_e32 v72, v114, v66
	v_add_f32_e32 v67, v115, v67
	v_add_f32_e32 v112, v116, v72
	v_add_f32_e32 v113, v117, v67
	v_cvt_pk_bf16_f32 v66, v114, v115
	v_cvt_pk_bf16_f32 v67, v116, v117
	s_waitcnt lgkmcnt(2)
	v_mfma_f32_32x32x16_bf16 v[16:31], v[108:111], v[100:103], v[16:31]
	ds_read_b128 v[72:75], v210 offset:53312
	s_waitcnt lgkmcnt(2)
	v_mfma_f32_32x32x16_bf16 v[0:15], v[76:79], v[96:99], v[0:15]
	ds_read_b128 v[76:79], v210 offset:57920
	s_waitcnt lgkmcnt(2)
	v_mfma_f32_32x32x16_bf16 v[16:31], v[104:107], v[96:99], v[16:31]
	ds_read_b128 v[96:99], v210 offset:53344
	ds_read_b128 v[102:105], v210 offset:57952
	s_waitcnt lgkmcnt(3)
	v_mfma_f32_32x32x16_bf16 v[0:15], v[72:75], v[68:71], v[0:15]
	s_waitcnt lgkmcnt(2)
	v_mfma_f32_32x32x16_bf16 v[16:31], v[76:79], v[68:71], v[16:31]
	s_waitcnt lgkmcnt(1)
	v_mfma_f32_32x32x16_bf16 v[0:15], v[96:99], v[64:67], v[0:15]
	v_add_f32_e32 v221, v112, v113
	v_cmp_lt_f32_e32 vcc, s58, v221
	v_add_f32_e32 v100, v118, v221
	s_waitcnt lgkmcnt(0)
	v_mfma_f32_32x32x16_bf16 v[16:31], v[102:105], v[64:67], v[16:31]
	ds_read_b128 v[64:67], v181 offset:26624
	ds_read_b128 v[96:99], v181 offset:33280
	s_cbranch_vccnz .Lmla_rare_a_5

.LBB0_935:
	ds_read_b128 v[102:105], v181 offset:26656
	ds_read_b128 v[138:141], v181 offset:33312
	s_waitcnt lgkmcnt(3)
	v_mfma_f32_32x32x16_bf16 v[106:121], v[64:67], v[144:147], v[32:47]
	v_exp_f32_e32 v101, v122
	v_exp_f32_e32 v142, v123
	v_exp_f32_e32 v143, v124
	v_exp_f32_e32 v202, v125
	v_exp_f32_e32 v126, v126
	v_exp_f32_e32 v127, v127
	s_waitcnt lgkmcnt(2)
	v_mfma_f32_32x32x16_bf16 v[64:79], v[96:99], v[144:147], v[32:47]
	ds_read_b128 v[96:99], v181 offset:26688
	ds_read_b128 v[122:125], v181 offset:33344
	s_waitcnt lgkmcnt(3)
	v_mfma_f32_32x32x16_bf16 v[106:121], v[102:105], v[148:151], v[106:121]
	v_cvt_pk_bf16_f32 v102, v101, v142
	v_add_f32_e32 v101, v143, v101
	v_add_f32_e32 v104, v202, v142
	v_add_f32_e32 v101, v126, v101
	s_waitcnt lgkmcnt(2)
	v_mfma_f32_32x32x16_bf16 v[64:79], v[138:141], v[148:151], v[64:79]
	v_add_f32_e32 v105, v127, v104
	v_exp_f32_e32 v203, v128
	v_exp_f32_e32 v204, v129
	v_exp_f32_e32 v205, v130
	v_exp_f32_e32 v213, v131
	v_exp_f32_e32 v214, v132
	v_exp_f32_e32 v215, v133
	v_cvt_pk_bf16_f32 v103, v143, v202
	v_cvt_pk_bf16_f32 v104, v126, v127
	ds_read_b128 v[126:129], v181 offset:26720
	ds_read_b128 v[130:133], v181 offset:33376
	s_waitcnt lgkmcnt(3)
	v_mfma_f32_32x32x16_bf16 v[106:121], v[96:99], v[152:155], v[106:121]
	v_add_f32_e32 v96, v203, v101
	v_add_f32_e32 v97, v204, v105
	v_add_f32_e32 v98, v205, v96
	v_add_f32_e32 v97, v213, v97
	v_add_f32_e32 v98, v214, v98
	v_add_f32_e32 v99, v215, v97
	s_waitcnt lgkmcnt(2)
	v_mfma_f32_32x32x16_bf16 v[64:79], v[122:125], v[152:155], v[64:79]
	v_exp_f32_e32 v138, v134
	v_exp_f32_e32 v139, v135
	v_exp_f32_e32 v140, v136
	v_exp_f32_e32 v141, v137
	v_cvt_pk_bf16_f32 v105, v203, v204
	v_cvt_pk_bf16_f32 v96, v205, v213
	v_cvt_pk_bf16_f32 v97, v214, v215
	ds_read_b128 v[122:125], v181 offset:26752
	ds_read_b128 v[134:137], v181 offset:33408
	s_waitcnt lgkmcnt(3)
	v_mfma_f32_32x32x16_bf16 v[106:121], v[126:129], v[156:159], v[106:121]
	v_exp_f32_e32 v101, v80
	v_exp_f32_e32 v142, v81
	v_add_f32_e32 v80, v138, v98
	v_add_f32_e32 v81, v139, v99
	v_exp_f32_e32 v203, v84
	v_exp_f32_e32 v204, v85
	s_waitcnt lgkmcnt(2)
	v_mfma_f32_32x32x16_bf16 v[64:79], v[130:133], v[156:159], v[64:79]
	v_add_f32_e32 v84, v140, v80
	v_add_f32_e32 v85, v141, v81
	v_exp_f32_e32 v143, v82
	v_exp_f32_e32 v202, v83
	v_cvt_pk_bf16_f32 v98, v138, v139
	v_cvt_pk_bf16_f32 v99, v140, v141
	ds_read_b128 v[80:83], v181 offset:26784
	ds_read_b128 v[126:129], v181 offset:33440
	s_waitcnt lgkmcnt(3)
	v_mfma_f32_32x32x16_bf16 v[106:121], v[122:125], v[160:163], v[106:121]
	v_exp_f32_e32 v87, v87
	v_exp_f32_e32 v130, v86
	v_add_f32_e32 v86, v101, v84
	v_add_f32_e32 v85, v142, v85
	v_exp_f32_e32 v131, v88
	v_add_f32_e32 v86, v143, v86
	s_waitcnt lgkmcnt(2)
	v_mfma_f32_32x32x16_bf16 v[64:79], v[134:137], v[160:163], v[64:79]
	v_add_f32_e32 v88, v202, v85
	v_cvt_pk_bf16_f32 v84, v101, v142
	v_add_f32_e32 v101, v203, v86
	v_add_f32_e32 v134, v204, v88
	v_exp_f32_e32 v132, v89
	v_exp_f32_e32 v133, v90
	v_exp_f32_e32 v138, v91
	v_cvt_pk_bf16_f32 v85, v143, v202
	v_cvt_pk_bf16_f32 v86, v203, v204
	ds_read_b128 v[88:91], v210 offset:62464
	ds_read_b128 v[122:125], v211 offset:13824
	s_waitcnt lgkmcnt(3)
	v_mfma_f32_32x32x16_bf16 v[106:121], v[80:83], v[164:167], v[106:121]
	v_add_f32_e32 v80, v130, v101
	v_add_f32_e32 v81, v87, v134
	v_add_f32_e32 v82, v131, v80
	v_add_f32_e32 v81, v132, v81
	v_add_f32_e32 v82, v133, v82
	v_add_f32_e32 v83, v138, v81
	s_waitcnt lgkmcnt(2)
	v_mfma_f32_32x32x16_bf16 v[64:79], v[126:129], v[164:167], v[64:79]
	v_exp_f32_e32 v135, v92
	v_exp_f32_e32 v136, v93
	v_exp_f32_e32 v137, v94
	v_exp_f32_e32 v139, v95
	v_cvt_pk_bf16_f32 v87, v130, v87
	v_cvt_pk_bf16_f32 v80, v131, v132
	v_cvt_pk_bf16_f32 v81, v133, v138
	ds_read_b128 v[92:95], v210 offset:62496
	ds_read_b128 v[126:129], v211 offset:13856
	s_waitcnt lgkmcnt(3)
	v_mfma_f32_32x32x16_bf16 v[0:15], v[88:91], v[102:105], v[0:15]
	v_add_f32_e32 v88, v135, v82
	v_add_f32_e32 v83, v136, v83
	v_add_f32_e32 v101, v137, v88
	v_add_f32_e32 v130, v139, v83
	v_cvt_pk_bf16_f32 v82, v135, v136
	v_cvt_pk_bf16_f32 v83, v137, v139
	s_waitcnt lgkmcnt(2)
	v_mfma_f32_32x32x16_bf16 v[16:31], v[122:125], v[102:105], v[16:31]
	ds_read_b128 v[88:91], v210 offset:62528
	s_waitcnt lgkmcnt(2)
	v_mfma_f32_32x32x16_bf16 v[0:15], v[92:95], v[96:99], v[0:15]
	ds_read_b128 v[92:95], v211 offset:13888
	s_waitcnt lgkmcnt(2)
	v_mfma_f32_32x32x16_bf16 v[16:31], v[126:129], v[96:99], v[16:31]
	ds_read_b128 v[96:99], v210 offset:62560
	ds_read_b128 v[102:105], v211 offset:13920
	s_waitcnt lgkmcnt(3)
	v_mfma_f32_32x32x16_bf16 v[0:15], v[88:91], v[84:87], v[0:15]
	s_waitcnt lgkmcnt(2)
	v_mfma_f32_32x32x16_bf16 v[16:31], v[92:95], v[84:87], v[16:31]
	s_waitcnt lgkmcnt(1)
	v_mfma_f32_32x32x16_bf16 v[0:15], v[96:99], v[80:83], v[0:15]
	v_add_f32_e32 v221, v101, v130
	v_cmp_lt_f32_e32 vcc, s58, v221
	v_add_f32_e32 v88, v100, v221
	s_waitcnt lgkmcnt(0)
	v_mfma_f32_32x32x16_bf16 v[16:31], v[102:105], v[80:83], v[16:31]
	s_waitcnt vmcnt(0)
	s_barrier
	ds_read_b128 v[84:87], v181 offset:39936
	ds_read_b128 v[80:83], v181 offset:46592
	s_cbranch_vccnz .Lmla_rare_a_6

.LBB0_941:
	s_waitcnt lgkmcnt(1)
	v_mfma_f32_32x32x16_bf16 v[122:137], v[84:87], v[144:147], v[32:47]
	v_exp_f32_e32 v89, v106
	v_exp_f32_e32 v94, v107
	v_exp_f32_e32 v95, v108
	v_exp_f32_e32 v142, v109
	v_exp_f32_e32 v143, v110
	v_exp_f32_e32 v202, v111
	ds_read_b128 v[84:87], v181 offset:39968
	ds_read_b128 v[90:93], v181 offset:46624
	s_waitcnt lgkmcnt(2)
	v_mfma_f32_32x32x16_bf16 v[96:111], v[80:83], v[144:147], v[32:47]
	ds_read_b128 v[80:83], v181 offset:40000
	ds_read_b128 v[138:141], v181 offset:46656
	s_waitcnt lgkmcnt(3)
	v_mfma_f32_32x32x16_bf16 v[122:137], v[84:87], v[148:151], v[122:137]
	v_exp_f32_e32 v116, v116
	v_add_f32_e32 v87, v95, v89
	v_add_f32_e32 v86, v142, v94
	v_cvt_pk_bf16_f32 v84, v89, v94
	s_waitcnt lgkmcnt(2)
	v_mfma_f32_32x32x16_bf16 v[96:111], v[90:93], v[148:151], v[96:111]
	v_add_f32_e32 v87, v143, v87
	v_add_f32_e32 v89, v202, v86
	v_exp_f32_e32 v203, v112
	v_exp_f32_e32 v204, v113
	v_exp_f32_e32 v205, v114
	v_exp_f32_e32 v213, v115
	v_exp_f32_e32 v117, v117
	v_cvt_pk_bf16_f32 v85, v95, v142
	v_cvt_pk_bf16_f32 v86, v143, v202
	ds_read_b128 v[90:93], v181 offset:40032
	ds_read_b128 v[112:115], v181 offset:46688
	s_waitcnt lgkmcnt(3)
	v_mfma_f32_32x32x16_bf16 v[122:137], v[80:83], v[152:155], v[122:137]
	v_add_f32_e32 v80, v203, v87
	v_add_f32_e32 v81, v204, v89
	v_add_f32_e32 v82, v205, v80
	v_add_f32_e32 v81, v213, v81
	v_add_f32_e32 v82, v116, v82
	v_add_f32_e32 v83, v117, v81
	s_waitcnt lgkmcnt(2)
	v_mfma_f32_32x32x16_bf16 v[96:111], v[138:141], v[152:155], v[96:111]
	v_exp_f32_e32 v94, v118
	v_exp_f32_e32 v95, v119
	v_exp_f32_e32 v120, v120
	v_exp_f32_e32 v121, v121
	v_cvt_pk_bf16_f32 v87, v203, v204
	v_cvt_pk_bf16_f32 v80, v205, v213
	v_cvt_pk_bf16_f32 v81, v116, v117
	ds_read_b128 v[116:119], v181 offset:40064
	ds_read_b128 v[138:141], v181 offset:46720
	s_waitcnt lgkmcnt(3)
	v_mfma_f32_32x32x16_bf16 v[122:137], v[90:93], v[156:159], v[122:137]
	v_exp_f32_e32 v89, v64
	v_exp_f32_e32 v142, v65
	v_add_f32_e32 v64, v94, v82
	v_add_f32_e32 v65, v95, v83
	v_exp_f32_e32 v203, v68
	v_exp_f32_e32 v204, v69
	s_waitcnt lgkmcnt(2)
	v_mfma_f32_32x32x16_bf16 v[96:111], v[112:115], v[156:159], v[96:111]
	v_add_f32_e32 v68, v120, v64
	v_add_f32_e32 v69, v121, v65
	v_exp_f32_e32 v143, v66
	v_exp_f32_e32 v202, v67
	v_cvt_pk_bf16_f32 v82, v94, v95
	v_cvt_pk_bf16_f32 v83, v120, v121
	ds_read_b128 v[64:67], v181 offset:40096
	ds_read_b128 v[90:93], v181 offset:46752
	s_waitcnt lgkmcnt(3)
	v_mfma_f32_32x32x16_bf16 v[122:137], v[116:119], v[160:163], v[122:137]
	v_exp_f32_e32 v116, v74
	v_exp_f32_e32 v94, v70
	v_add_f32_e32 v70, v89, v68
	v_add_f32_e32 v69, v142, v69
	v_exp_f32_e32 v95, v72
	v_add_f32_e32 v70, v143, v70
	s_waitcnt lgkmcnt(2)
	v_mfma_f32_32x32x16_bf16 v[96:111], v[138:141], v[160:163], v[96:111]
	v_add_f32_e32 v72, v202, v69
	v_cvt_pk_bf16_f32 v68, v89, v142
	v_add_f32_e32 v89, v203, v70
	v_add_f32_e32 v118, v204, v72
	v_exp_f32_e32 v71, v71
	v_exp_f32_e32 v120, v73
	v_exp_f32_e32 v117, v75
	v_cvt_pk_bf16_f32 v69, v143, v202
	v_cvt_pk_bf16_f32 v70, v203, v204
	ds_read_b128 v[72:75], v211 offset:18432
	ds_read_b128 v[112:115], v211 offset:23040
	s_waitcnt lgkmcnt(3)
	v_mfma_f32_32x32x16_bf16 v[122:137], v[64:67], v[164:167], v[122:137]
	v_add_f32_e32 v64, v94, v89
	v_add_f32_e32 v65, v71, v118
	v_add_f32_e32 v66, v95, v64
	v_add_f32_e32 v65, v120, v65
	v_add_f32_e32 v66, v116, v66
	v_add_f32_e32 v67, v117, v65
	s_waitcnt lgkmcnt(2)
	v_mfma_f32_32x32x16_bf16 v[96:111], v[90:93], v[164:167], v[96:111]
	v_exp_f32_e32 v119, v76
	v_exp_f32_e32 v121, v77
	v_exp_f32_e32 v138, v78
	v_exp_f32_e32 v139, v79
	v_cvt_pk_bf16_f32 v71, v94, v71
	v_cvt_pk_bf16_f32 v64, v95, v120
	v_cvt_pk_bf16_f32 v65, v116, v117
	ds_read_b128 v[76:79], v211 offset:18464
	ds_read_b128 v[90:93], v211 offset:23072
	s_waitcnt lgkmcnt(3)
	v_mfma_f32_32x32x16_bf16 v[0:15], v[72:75], v[84:87], v[0:15]
	v_add_f32_e32 v72, v119, v66
	v_add_f32_e32 v67, v121, v67
	v_add_f32_e32 v89, v138, v72
	v_add_f32_e32 v94, v139, v67
	v_cvt_pk_bf16_f32 v66, v119, v121
	v_cvt_pk_bf16_f32 v67, v138, v139
	s_waitcnt lgkmcnt(2)
	v_mfma_f32_32x32x16_bf16 v[16:31], v[112:115], v[84:87], v[16:31]
	ds_read_b128 v[72:75], v211 offset:18496
	s_waitcnt lgkmcnt(2)
	v_mfma_f32_32x32x16_bf16 v[0:15], v[76:79], v[80:83], v[0:15]
	ds_read_b128 v[76:79], v211 offset:23104
	s_waitcnt lgkmcnt(2)
	v_mfma_f32_32x32x16_bf16 v[16:31], v[90:93], v[80:83], v[16:31]
	ds_read_b128 v[80:83], v211 offset:18528
	ds_read_b128 v[84:87], v211 offset:23136
	s_waitcnt lgkmcnt(3)
	v_mfma_f32_32x32x16_bf16 v[0:15], v[72:75], v[68:71], v[0:15]
	s_waitcnt lgkmcnt(2)
	v_mfma_f32_32x32x16_bf16 v[16:31], v[76:79], v[68:71], v[16:31]
	s_waitcnt lgkmcnt(1)
	v_mfma_f32_32x32x16_bf16 v[0:15], v[80:83], v[64:67], v[0:15]
	v_add_f32_e32 v221, v89, v94
	v_cmp_lt_f32_e32 vcc, s58, v221
	v_add_f32_e32 v116, v88, v221
	s_waitcnt lgkmcnt(0)
	v_mfma_f32_32x32x16_bf16 v[16:31], v[84:87], v[64:67], v[16:31]
	ds_read_b128 v[64:67], v181
	ds_read_b128 v[112:115], v181 offset:6656
	s_cbranch_vccnz .Lmla_rare_a_7

.Lmla_rare_a_1:
	v_mov_b32_e32 v222, v221
	v_mov_b32_e32 v223, v221
	s_nop 1
	v_permlane32_swap_b32_e32 v222, v223
	v_add_f32_e32 v222, v222, v223
	v_log_f32_e32 v222, v222
	s_nop 0
	v_max_f32_e32 v33, 0, v222
	v_exp_f32_e64 v34, -v33
	v_add_f32_e32 v212, v212, v33
	v_xor_b32_e32 v32, 0x80000000, v212
	v_sub_f32_e32 v143, v143, v33
	v_pk_mul_f32 v[14:15], v[14:15], v[34:35] op_sel_hi:[1,0]
	v_pk_mul_f32 v[12:13], v[12:13], v[34:35] op_sel_hi:[1,0]
	v_pk_mul_f32 v[10:11], v[10:11], v[34:35] op_sel_hi:[1,0]
	v_pk_mul_f32 v[8:9], v[8:9], v[34:35] op_sel_hi:[1,0]
	v_pk_mul_f32 v[6:7], v[6:7], v[34:35] op_sel_hi:[1,0]
	v_pk_mul_f32 v[4:5], v[4:5], v[34:35] op_sel_hi:[1,0]
	v_pk_mul_f32 v[2:3], v[2:3], v[34:35] op_sel_hi:[1,0]
	v_pk_mul_f32 v[0:1], v[0:1], v[34:35] op_sel_hi:[1,0]
	v_pk_mul_f32 v[30:31], v[30:31], v[34:35] op_sel_hi:[1,0]
	v_pk_mul_f32 v[28:29], v[28:29], v[34:35] op_sel_hi:[1,0]
	v_pk_mul_f32 v[26:27], v[26:27], v[34:35] op_sel_hi:[1,0]
	v_pk_mul_f32 v[24:25], v[24:25], v[34:35] op_sel_hi:[1,0]
	v_pk_mul_f32 v[22:23], v[22:23], v[34:35] op_sel_hi:[1,0]
	v_pk_mul_f32 v[20:21], v[20:21], v[34:35] op_sel_hi:[1,0]
	v_pk_mul_f32 v[18:19], v[18:19], v[34:35] op_sel_hi:[1,0]
	v_pk_mul_f32 v[16:17], v[16:17], v[34:35] op_sel_hi:[1,0]
	v_sub_f32_e32 v142, v142, v33
	v_sub_f32_e32 v141, v141, v33
	v_sub_f32_e32 v140, v140, v33
	v_sub_f32_e32 v139, v139, v33
	v_sub_f32_e32 v138, v138, v33
	v_sub_f32_e32 v137, v137, v33
	v_sub_f32_e32 v136, v136, v33
	v_sub_f32_e32 v135, v135, v33
	v_sub_f32_e32 v134, v134, v33
	v_sub_f32_e32 v133, v133, v33
	v_sub_f32_e32 v132, v132, v33
	v_sub_f32_e32 v131, v131, v33
	v_sub_f32_e32 v130, v130, v33
	v_sub_f32_e32 v129, v129, v33
	v_sub_f32_e32 v128, v128, v33
	v_sub_f32_e32 v111, v111, v33
	v_sub_f32_e32 v110, v110, v33
	v_sub_f32_e32 v109, v109, v33
	v_sub_f32_e32 v108, v108, v33
	v_sub_f32_e32 v107, v107, v33
	v_sub_f32_e32 v106, v106, v33
	v_sub_f32_e32 v105, v105, v33
	v_sub_f32_e32 v104, v104, v33
	v_sub_f32_e32 v103, v103, v33
	v_sub_f32_e32 v102, v102, v33
	v_sub_f32_e32 v101, v101, v33
	v_sub_f32_e32 v100, v100, v33
	v_sub_f32_e32 v99, v99, v33
	v_sub_f32_e32 v98, v98, v33
	v_sub_f32_e32 v97, v97, v33
	v_sub_f32_e32 v96, v96, v33
	v_mul_f32_e32 v86, v86, v34
	v_mov_b32_e32 v33, v32
	v_mov_b32_e32 v34, v32
	v_mov_b32_e32 v35, v32
	v_mov_b32_e32 v36, v32
	v_mov_b32_e32 v37, v32
	v_mov_b32_e32 v38, v32
	v_mov_b32_e32 v39, v32
	v_mov_b32_e32 v40, v32
	v_mov_b32_e32 v41, v32
	v_mov_b32_e32 v42, v32
	v_mov_b32_e32 v43, v32
	v_mov_b32_e32 v44, v32
	v_mov_b32_e32 v45, v32
	v_mov_b32_e32 v46, v32
	v_mov_b32_e32 v47, v32
	v_mov_b32_e32 v48, v32
	v_mov_b32_e32 v49, v32
	v_mov_b32_e32 v50, v32
	v_mov_b32_e32 v51, v32
	v_mov_b32_e32 v52, v32
	v_mov_b32_e32 v53, v32
	v_mov_b32_e32 v54, v32
	v_mov_b32_e32 v55, v32
	v_mov_b32_e32 v56, v32
	v_mov_b32_e32 v57, v32
	v_mov_b32_e32 v58, v32
	v_mov_b32_e32 v59, v32
	v_mov_b32_e32 v60, v32
	v_mov_b32_e32 v61, v32
	v_mov_b32_e32 v62, v32
	v_mov_b32_e32 v63, v32
	s_branch .LBB0_907
.Lmla_rare_a_2:
	v_mov_b32_e32 v222, v221
	v_mov_b32_e32 v223, v221
	s_nop 1
	v_permlane32_swap_b32_e32 v222, v223
	v_add_f32_e32 v222, v222, v223
	v_log_f32_e32 v222, v222
	s_nop 0
	v_max_f32_e32 v33, 0, v222
	v_exp_f32_e64 v34, -v33
	v_add_f32_e32 v212, v212, v33
	v_xor_b32_e32 v32, 0x80000000, v212
	v_sub_f32_e32 v127, v127, v33
	v_pk_mul_f32 v[14:15], v[14:15], v[34:35] op_sel_hi:[1,0]
	v_pk_mul_f32 v[12:13], v[12:13], v[34:35] op_sel_hi:[1,0]
	v_pk_mul_f32 v[10:11], v[10:11], v[34:35] op_sel_hi:[1,0]
	v_pk_mul_f32 v[8:9], v[8:9], v[34:35] op_sel_hi:[1,0]
	v_pk_mul_f32 v[6:7], v[6:7], v[34:35] op_sel_hi:[1,0]
	v_pk_mul_f32 v[4:5], v[4:5], v[34:35] op_sel_hi:[1,0]
	v_pk_mul_f32 v[2:3], v[2:3], v[34:35] op_sel_hi:[1,0]
	v_pk_mul_f32 v[0:1], v[0:1], v[34:35] op_sel_hi:[1,0]
	v_pk_mul_f32 v[30:31], v[30:31], v[34:35] op_sel_hi:[1,0]
	v_pk_mul_f32 v[28:29], v[28:29], v[34:35] op_sel_hi:[1,0]
	v_pk_mul_f32 v[26:27], v[26:27], v[34:35] op_sel_hi:[1,0]
	v_pk_mul_f32 v[24:25], v[24:25], v[34:35] op_sel_hi:[1,0]
	v_pk_mul_f32 v[22:23], v[22:23], v[34:35] op_sel_hi:[1,0]
	v_pk_mul_f32 v[20:21], v[20:21], v[34:35] op_sel_hi:[1,0]
	v_pk_mul_f32 v[18:19], v[18:19], v[34:35] op_sel_hi:[1,0]
	v_pk_mul_f32 v[16:17], v[16:17], v[34:35] op_sel_hi:[1,0]
	v_sub_f32_e32 v126, v126, v33
	v_sub_f32_e32 v125, v125, v33
	v_sub_f32_e32 v124, v124, v33
	v_sub_f32_e32 v123, v123, v33
	v_sub_f32_e32 v122, v122, v33
	v_sub_f32_e32 v121, v121, v33
	v_sub_f32_e32 v120, v120, v33
	v_sub_f32_e32 v119, v119, v33
	v_sub_f32_e32 v118, v118, v33
	v_sub_f32_e32 v117, v117, v33
	v_sub_f32_e32 v116, v116, v33
	v_sub_f32_e32 v115, v115, v33
	v_sub_f32_e32 v114, v114, v33
	v_sub_f32_e32 v113, v113, v33
	v_sub_f32_e32 v112, v112, v33
	v_sub_f32_e32 v79, v79, v33
	v_sub_f32_e32 v78, v78, v33
	v_sub_f32_e32 v77, v77, v33
	v_sub_f32_e32 v76, v76, v33
	v_sub_f32_e32 v75, v75, v33
	v_sub_f32_e32 v74, v74, v33
	v_sub_f32_e32 v73, v73, v33
	v_sub_f32_e32 v72, v72, v33
	v_sub_f32_e32 v71, v71, v33
	v_sub_f32_e32 v70, v70, v33
	v_sub_f32_e32 v69, v69, v33
	v_sub_f32_e32 v68, v68, v33
	v_sub_f32_e32 v67, v67, v33
	v_sub_f32_e32 v66, v66, v33
	v_sub_f32_e32 v65, v65, v33
	v_sub_f32_e32 v64, v64, v33
	v_mul_f32_e32 v102, v102, v34
	v_mov_b32_e32 v33, v32
	v_mov_b32_e32 v34, v32
	v_mov_b32_e32 v35, v32
	v_mov_b32_e32 v36, v32
	v_mov_b32_e32 v37, v32
	v_mov_b32_e32 v38, v32
	v_mov_b32_e32 v39, v32
	v_mov_b32_e32 v40, v32
	v_mov_b32_e32 v41, v32
	v_mov_b32_e32 v42, v32
	v_mov_b32_e32 v43, v32
	v_mov_b32_e32 v44, v32
	v_mov_b32_e32 v45, v32
	v_mov_b32_e32 v46, v32
	v_mov_b32_e32 v47, v32
	v_mov_b32_e32 v48, v32
	v_mov_b32_e32 v49, v32
	v_mov_b32_e32 v50, v32
	v_mov_b32_e32 v51, v32
	v_mov_b32_e32 v52, v32
	v_mov_b32_e32 v53, v32
	v_mov_b32_e32 v54, v32
	v_mov_b32_e32 v55, v32
	v_mov_b32_e32 v56, v32
	v_mov_b32_e32 v57, v32
	v_mov_b32_e32 v58, v32
	v_mov_b32_e32 v59, v32
	v_mov_b32_e32 v60, v32
	v_mov_b32_e32 v61, v32
	v_mov_b32_e32 v62, v32
	v_mov_b32_e32 v63, v32
	s_branch .LBB0_913
.Lmla_rare_a_3:
	v_mov_b32_e32 v222, v221
	v_mov_b32_e32 v223, v221
	s_nop 1
	v_permlane32_swap_b32_e32 v222, v223
	v_add_f32_e32 v222, v222, v223
	v_log_f32_e32 v222, v222
	s_nop 0
	v_max_f32_e32 v33, 0, v222
	v_exp_f32_e64 v34, -v33
	v_add_f32_e32 v212, v212, v33
	v_xor_b32_e32 v32, 0x80000000, v212
	v_sub_f32_e32 v143, v143, v33
	v_pk_mul_f32 v[14:15], v[14:15], v[34:35] op_sel_hi:[1,0]
	v_pk_mul_f32 v[12:13], v[12:13], v[34:35] op_sel_hi:[1,0]
	v_pk_mul_f32 v[10:11], v[10:11], v[34:35] op_sel_hi:[1,0]
	v_pk_mul_f32 v[8:9], v[8:9], v[34:35] op_sel_hi:[1,0]
	v_pk_mul_f32 v[6:7], v[6:7], v[34:35] op_sel_hi:[1,0]
	v_pk_mul_f32 v[4:5], v[4:5], v[34:35] op_sel_hi:[1,0]
	v_pk_mul_f32 v[2:3], v[2:3], v[34:35] op_sel_hi:[1,0]
	v_pk_mul_f32 v[0:1], v[0:1], v[34:35] op_sel_hi:[1,0]
	v_pk_mul_f32 v[30:31], v[30:31], v[34:35] op_sel_hi:[1,0]
	v_pk_mul_f32 v[28:29], v[28:29], v[34:35] op_sel_hi:[1,0]
	v_pk_mul_f32 v[26:27], v[26:27], v[34:35] op_sel_hi:[1,0]
	v_pk_mul_f32 v[24:25], v[24:25], v[34:35] op_sel_hi:[1,0]
	v_pk_mul_f32 v[22:23], v[22:23], v[34:35] op_sel_hi:[1,0]
	v_pk_mul_f32 v[20:21], v[20:21], v[34:35] op_sel_hi:[1,0]
	v_pk_mul_f32 v[18:19], v[18:19], v[34:35] op_sel_hi:[1,0]
	v_pk_mul_f32 v[16:17], v[16:17], v[34:35] op_sel_hi:[1,0]
	v_sub_f32_e32 v142, v142, v33
	v_sub_f32_e32 v141, v141, v33
	v_sub_f32_e32 v140, v140, v33
	v_sub_f32_e32 v139, v139, v33
	v_sub_f32_e32 v138, v138, v33
	v_sub_f32_e32 v137, v137, v33
	v_sub_f32_e32 v136, v136, v33
	v_sub_f32_e32 v135, v135, v33
	v_sub_f32_e32 v134, v134, v33
	v_sub_f32_e32 v133, v133, v33
	v_sub_f32_e32 v132, v132, v33
	v_sub_f32_e32 v131, v131, v33
	v_sub_f32_e32 v130, v130, v33
	v_sub_f32_e32 v129, v129, v33
	v_sub_f32_e32 v128, v128, v33
	v_sub_f32_e32 v95, v95, v33
	v_sub_f32_e32 v94, v94, v33
	v_sub_f32_e32 v93, v93, v33
	v_sub_f32_e32 v92, v92, v33
	v_sub_f32_e32 v91, v91, v33
	v_sub_f32_e32 v90, v90, v33
	v_sub_f32_e32 v89, v89, v33
	v_sub_f32_e32 v88, v88, v33
	v_sub_f32_e32 v87, v87, v33
	v_sub_f32_e32 v86, v86, v33
	v_sub_f32_e32 v85, v85, v33
	v_sub_f32_e32 v84, v84, v33
	v_sub_f32_e32 v83, v83, v33
	v_sub_f32_e32 v82, v82, v33
	v_sub_f32_e32 v81, v81, v33
	v_sub_f32_e32 v80, v80, v33
	v_mul_f32_e32 v118, v118, v34
	v_mov_b32_e32 v33, v32
	v_mov_b32_e32 v34, v32
	v_mov_b32_e32 v35, v32
	v_mov_b32_e32 v36, v32
	v_mov_b32_e32 v37, v32
	v_mov_b32_e32 v38, v32
	v_mov_b32_e32 v39, v32
	v_mov_b32_e32 v40, v32
	v_mov_b32_e32 v41, v32
	v_mov_b32_e32 v42, v32
	v_mov_b32_e32 v43, v32
	v_mov_b32_e32 v44, v32
	v_mov_b32_e32 v45, v32
	v_mov_b32_e32 v46, v32
	v_mov_b32_e32 v47, v32
	v_mov_b32_e32 v48, v32
	v_mov_b32_e32 v49, v32
	v_mov_b32_e32 v50, v32
	v_mov_b32_e32 v51, v32
	v_mov_b32_e32 v52, v32
	v_mov_b32_e32 v53, v32
	v_mov_b32_e32 v54, v32
	v_mov_b32_e32 v55, v32
	v_mov_b32_e32 v56, v32
	v_mov_b32_e32 v57, v32
	v_mov_b32_e32 v58, v32
	v_mov_b32_e32 v59, v32
	v_mov_b32_e32 v60, v32
	v_mov_b32_e32 v61, v32
	v_mov_b32_e32 v62, v32
	v_mov_b32_e32 v63, v32
	s_branch .LBB0_919
.Lmla_rare_a_4:
	v_mov_b32_e32 v222, v221
	v_mov_b32_e32 v223, v221
	s_nop 1
	v_permlane32_swap_b32_e32 v222, v223
	v_add_f32_e32 v222, v222, v223
	v_log_f32_e32 v222, v222
	s_nop 0
	v_max_f32_e32 v33, 0, v222
	v_exp_f32_e64 v34, -v33
	v_add_f32_e32 v212, v212, v33
	v_xor_b32_e32 v32, 0x80000000, v212
	v_sub_f32_e32 v111, v111, v33
	v_pk_mul_f32 v[14:15], v[14:15], v[34:35] op_sel_hi:[1,0]
	v_pk_mul_f32 v[12:13], v[12:13], v[34:35] op_sel_hi:[1,0]
	v_pk_mul_f32 v[10:11], v[10:11], v[34:35] op_sel_hi:[1,0]
	v_pk_mul_f32 v[8:9], v[8:9], v[34:35] op_sel_hi:[1,0]
	v_pk_mul_f32 v[6:7], v[6:7], v[34:35] op_sel_hi:[1,0]
	v_pk_mul_f32 v[4:5], v[4:5], v[34:35] op_sel_hi:[1,0]
	v_pk_mul_f32 v[2:3], v[2:3], v[34:35] op_sel_hi:[1,0]
	v_pk_mul_f32 v[0:1], v[0:1], v[34:35] op_sel_hi:[1,0]
	v_pk_mul_f32 v[30:31], v[30:31], v[34:35] op_sel_hi:[1,0]
	v_pk_mul_f32 v[28:29], v[28:29], v[34:35] op_sel_hi:[1,0]
	v_pk_mul_f32 v[26:27], v[26:27], v[34:35] op_sel_hi:[1,0]
	v_pk_mul_f32 v[24:25], v[24:25], v[34:35] op_sel_hi:[1,0]
	v_pk_mul_f32 v[22:23], v[22:23], v[34:35] op_sel_hi:[1,0]
	v_pk_mul_f32 v[20:21], v[20:21], v[34:35] op_sel_hi:[1,0]
	v_pk_mul_f32 v[18:19], v[18:19], v[34:35] op_sel_hi:[1,0]
	v_pk_mul_f32 v[16:17], v[16:17], v[34:35] op_sel_hi:[1,0]
	v_sub_f32_e32 v110, v110, v33
	v_sub_f32_e32 v109, v109, v33
	v_sub_f32_e32 v108, v108, v33
	v_sub_f32_e32 v107, v107, v33
	v_sub_f32_e32 v106, v106, v33
	v_sub_f32_e32 v105, v105, v33
	v_sub_f32_e32 v104, v104, v33
	v_sub_f32_e32 v103, v103, v33
	v_sub_f32_e32 v102, v102, v33
	v_sub_f32_e32 v101, v101, v33
	v_sub_f32_e32 v100, v100, v33
	v_sub_f32_e32 v99, v99, v33
	v_sub_f32_e32 v98, v98, v33
	v_sub_f32_e32 v97, v97, v33
	v_sub_f32_e32 v96, v96, v33
	v_sub_f32_e32 v79, v79, v33
	v_sub_f32_e32 v78, v78, v33
	v_sub_f32_e32 v77, v77, v33
	v_sub_f32_e32 v76, v76, v33
	v_sub_f32_e32 v75, v75, v33
	v_sub_f32_e32 v74, v74, v33
	v_sub_f32_e32 v73, v73, v33
	v_sub_f32_e32 v72, v72, v33
	v_sub_f32_e32 v71, v71, v33
	v_sub_f32_e32 v70, v70, v33
	v_sub_f32_e32 v69, v69, v33
	v_sub_f32_e32 v68, v68, v33
	v_sub_f32_e32 v67, v67, v33
	v_sub_f32_e32 v66, v66, v33
	v_sub_f32_e32 v65, v65, v33
	v_sub_f32_e32 v64, v64, v33
	v_mul_f32_e32 v118, v118, v34
	v_mov_b32_e32 v33, v32
	v_mov_b32_e32 v34, v32
	v_mov_b32_e32 v35, v32
	v_mov_b32_e32 v36, v32
	v_mov_b32_e32 v37, v32
	v_mov_b32_e32 v38, v32
	v_mov_b32_e32 v39, v32
	v_mov_b32_e32 v40, v32
	v_mov_b32_e32 v41, v32
	v_mov_b32_e32 v42, v32
	v_mov_b32_e32 v43, v32
	v_mov_b32_e32 v44, v32
	v_mov_b32_e32 v45, v32
	v_mov_b32_e32 v46, v32
	v_mov_b32_e32 v47, v32
	v_mov_b32_e32 v48, v32
	v_mov_b32_e32 v49, v32
	v_mov_b32_e32 v50, v32
	v_mov_b32_e32 v51, v32
	v_mov_b32_e32 v52, v32
	v_mov_b32_e32 v53, v32
	v_mov_b32_e32 v54, v32
	v_mov_b32_e32 v55, v32
	v_mov_b32_e32 v56, v32
	v_mov_b32_e32 v57, v32
	v_mov_b32_e32 v58, v32
	v_mov_b32_e32 v59, v32
	v_mov_b32_e32 v60, v32
	v_mov_b32_e32 v61, v32
	v_mov_b32_e32 v62, v32
	v_mov_b32_e32 v63, v32
	s_branch .LBB0_925
.Lmla_rare_a_5:
	v_mov_b32_e32 v222, v221
	v_mov_b32_e32 v223, v221
	s_nop 1
	v_permlane32_swap_b32_e32 v222, v223
	v_add_f32_e32 v222, v222, v223
	v_log_f32_e32 v222, v222
	s_nop 0
	v_max_f32_e32 v33, 0, v222
	v_exp_f32_e64 v34, -v33
	v_add_f32_e32 v212, v212, v33
	v_xor_b32_e32 v32, 0x80000000, v212
	v_sub_f32_e32 v137, v137, v33
	v_pk_mul_f32 v[14:15], v[14:15], v[34:35] op_sel_hi:[1,0]
	v_pk_mul_f32 v[12:13], v[12:13], v[34:35] op_sel_hi:[1,0]
	v_pk_mul_f32 v[10:11], v[10:11], v[34:35] op_sel_hi:[1,0]
	v_pk_mul_f32 v[8:9], v[8:9], v[34:35] op_sel_hi:[1,0]
	v_pk_mul_f32 v[6:7], v[6:7], v[34:35] op_sel_hi:[1,0]
	v_pk_mul_f32 v[4:5], v[4:5], v[34:35] op_sel_hi:[1,0]
	v_pk_mul_f32 v[2:3], v[2:3], v[34:35] op_sel_hi:[1,0]
	v_pk_mul_f32 v[0:1], v[0:1], v[34:35] op_sel_hi:[1,0]
	v_pk_mul_f32 v[30:31], v[30:31], v[34:35] op_sel_hi:[1,0]
	v_pk_mul_f32 v[28:29], v[28:29], v[34:35] op_sel_hi:[1,0]
	v_pk_mul_f32 v[26:27], v[26:27], v[34:35] op_sel_hi:[1,0]
	v_pk_mul_f32 v[24:25], v[24:25], v[34:35] op_sel_hi:[1,0]
	v_pk_mul_f32 v[22:23], v[22:23], v[34:35] op_sel_hi:[1,0]
	v_pk_mul_f32 v[20:21], v[20:21], v[34:35] op_sel_hi:[1,0]
	v_pk_mul_f32 v[18:19], v[18:19], v[34:35] op_sel_hi:[1,0]
	v_pk_mul_f32 v[16:17], v[16:17], v[34:35] op_sel_hi:[1,0]
	v_sub_f32_e32 v136, v136, v33
	v_sub_f32_e32 v135, v135, v33
	v_sub_f32_e32 v134, v134, v33
	v_sub_f32_e32 v133, v133, v33
	v_sub_f32_e32 v132, v132, v33
	v_sub_f32_e32 v131, v131, v33
	v_sub_f32_e32 v130, v130, v33
	v_sub_f32_e32 v129, v129, v33
	v_sub_f32_e32 v128, v128, v33
	v_sub_f32_e32 v127, v127, v33
	v_sub_f32_e32 v126, v126, v33
	v_sub_f32_e32 v125, v125, v33
	v_sub_f32_e32 v124, v124, v33
	v_sub_f32_e32 v123, v123, v33
	v_sub_f32_e32 v122, v122, v33
	v_sub_f32_e32 v95, v95, v33
	v_sub_f32_e32 v94, v94, v33
	v_sub_f32_e32 v93, v93, v33
	v_sub_f32_e32 v92, v92, v33
	v_sub_f32_e32 v91, v91, v33
	v_sub_f32_e32 v90, v90, v33
	v_sub_f32_e32 v89, v89, v33
	v_sub_f32_e32 v88, v88, v33
	v_sub_f32_e32 v87, v87, v33
	v_sub_f32_e32 v86, v86, v33
	v_sub_f32_e32 v85, v85, v33
	v_sub_f32_e32 v84, v84, v33
	v_sub_f32_e32 v83, v83, v33
	v_sub_f32_e32 v82, v82, v33
	v_sub_f32_e32 v81, v81, v33
	v_sub_f32_e32 v80, v80, v33
	v_mul_f32_e32 v100, v100, v34
	v_mov_b32_e32 v33, v32
	v_mov_b32_e32 v34, v32
	v_mov_b32_e32 v35, v32
	v_mov_b32_e32 v36, v32
	v_mov_b32_e32 v37, v32
	v_mov_b32_e32 v38, v32
	v_mov_b32_e32 v39, v32
	v_mov_b32_e32 v40, v32
	v_mov_b32_e32 v41, v32
	v_mov_b32_e32 v42, v32
	v_mov_b32_e32 v43, v32
	v_mov_b32_e32 v44, v32
	v_mov_b32_e32 v45, v32
	v_mov_b32_e32 v46, v32
	v_mov_b32_e32 v47, v32
	v_mov_b32_e32 v48, v32
	v_mov_b32_e32 v49, v32
	v_mov_b32_e32 v50, v32
	v_mov_b32_e32 v51, v32
	v_mov_b32_e32 v52, v32
	v_mov_b32_e32 v53, v32
	v_mov_b32_e32 v54, v32
	v_mov_b32_e32 v55, v32
	v_mov_b32_e32 v56, v32
	v_mov_b32_e32 v57, v32
	v_mov_b32_e32 v58, v32
	v_mov_b32_e32 v59, v32
	v_mov_b32_e32 v60, v32
	v_mov_b32_e32 v61, v32
	v_mov_b32_e32 v62, v32
	v_mov_b32_e32 v63, v32
	s_branch .LBB0_931
.Lmla_rare_a_6:
	v_mov_b32_e32 v222, v221
	v_mov_b32_e32 v223, v221
	s_nop 1
	v_permlane32_swap_b32_e32 v222, v223
	v_add_f32_e32 v222, v222, v223
	v_log_f32_e32 v222, v222
	s_nop 0
	v_max_f32_e32 v33, 0, v222
	v_exp_f32_e64 v34, -v33
	v_add_f32_e32 v212, v212, v33
	v_xor_b32_e32 v32, 0x80000000, v212
	v_sub_f32_e32 v121, v121, v33
	v_pk_mul_f32 v[14:15], v[14:15], v[34:35] op_sel_hi:[1,0]
	v_pk_mul_f32 v[12:13], v[12:13], v[34:35] op_sel_hi:[1,0]
	v_pk_mul_f32 v[10:11], v[10:11], v[34:35] op_sel_hi:[1,0]
	v_pk_mul_f32 v[8:9], v[8:9], v[34:35] op_sel_hi:[1,0]
	v_pk_mul_f32 v[6:7], v[6:7], v[34:35] op_sel_hi:[1,0]
	v_pk_mul_f32 v[4:5], v[4:5], v[34:35] op_sel_hi:[1,0]
	v_pk_mul_f32 v[2:3], v[2:3], v[34:35] op_sel_hi:[1,0]
	v_pk_mul_f32 v[0:1], v[0:1], v[34:35] op_sel_hi:[1,0]
	v_pk_mul_f32 v[30:31], v[30:31], v[34:35] op_sel_hi:[1,0]
	v_pk_mul_f32 v[28:29], v[28:29], v[34:35] op_sel_hi:[1,0]
	v_pk_mul_f32 v[26:27], v[26:27], v[34:35] op_sel_hi:[1,0]
	v_pk_mul_f32 v[24:25], v[24:25], v[34:35] op_sel_hi:[1,0]
	v_pk_mul_f32 v[22:23], v[22:23], v[34:35] op_sel_hi:[1,0]
	v_pk_mul_f32 v[20:21], v[20:21], v[34:35] op_sel_hi:[1,0]
	v_pk_mul_f32 v[18:19], v[18:19], v[34:35] op_sel_hi:[1,0]
	v_pk_mul_f32 v[16:17], v[16:17], v[34:35] op_sel_hi:[1,0]
	v_sub_f32_e32 v120, v120, v33
	v_sub_f32_e32 v119, v119, v33
	v_sub_f32_e32 v118, v118, v33
	v_sub_f32_e32 v117, v117, v33
	v_sub_f32_e32 v116, v116, v33
	v_sub_f32_e32 v115, v115, v33
	v_sub_f32_e32 v114, v114, v33
	v_sub_f32_e32 v113, v113, v33
	v_sub_f32_e32 v112, v112, v33
	v_sub_f32_e32 v111, v111, v33
	v_sub_f32_e32 v110, v110, v33
	v_sub_f32_e32 v109, v109, v33
	v_sub_f32_e32 v108, v108, v33
	v_sub_f32_e32 v107, v107, v33
	v_sub_f32_e32 v106, v106, v33
	v_sub_f32_e32 v79, v79, v33
	v_sub_f32_e32 v78, v78, v33
	v_sub_f32_e32 v77, v77, v33
	v_sub_f32_e32 v76, v76, v33
	v_sub_f32_e32 v75, v75, v33
	v_sub_f32_e32 v74, v74, v33
	v_sub_f32_e32 v73, v73, v33
	v_sub_f32_e32 v72, v72, v33
	v_sub_f32_e32 v71, v71, v33
	v_sub_f32_e32 v70, v70, v33
	v_sub_f32_e32 v69, v69, v33
	v_sub_f32_e32 v68, v68, v33
	v_sub_f32_e32 v67, v67, v33
	v_sub_f32_e32 v66, v66, v33
	v_sub_f32_e32 v65, v65, v33
	v_sub_f32_e32 v64, v64, v33
	v_mul_f32_e32 v88, v88, v34
	v_mov_b32_e32 v33, v32
	v_mov_b32_e32 v34, v32
	v_mov_b32_e32 v35, v32
	v_mov_b32_e32 v36, v32
	v_mov_b32_e32 v37, v32
	v_mov_b32_e32 v38, v32
	v_mov_b32_e32 v39, v32
	v_mov_b32_e32 v40, v32
	v_mov_b32_e32 v41, v32
	v_mov_b32_e32 v42, v32
	v_mov_b32_e32 v43, v32
	v_mov_b32_e32 v44, v32
	v_mov_b32_e32 v45, v32
	v_mov_b32_e32 v46, v32
	v_mov_b32_e32 v47, v32
	v_mov_b32_e32 v48, v32
	v_mov_b32_e32 v49, v32
	v_mov_b32_e32 v50, v32
	v_mov_b32_e32 v51, v32
	v_mov_b32_e32 v52, v32
	v_mov_b32_e32 v53, v32
	v_mov_b32_e32 v54, v32
	v_mov_b32_e32 v55, v32
	v_mov_b32_e32 v56, v32
	v_mov_b32_e32 v57, v32
	v_mov_b32_e32 v58, v32
	v_mov_b32_e32 v59, v32
	v_mov_b32_e32 v60, v32
	v_mov_b32_e32 v61, v32
	v_mov_b32_e32 v62, v32
	v_mov_b32_e32 v63, v32
	s_branch .LBB0_937
.Lmla_rare_a_7:
	v_mov_b32_e32 v222, v221
	v_mov_b32_e32 v223, v221
	s_nop 1
	v_permlane32_swap_b32_e32 v222, v223
	v_add_f32_e32 v222, v222, v223
	v_log_f32_e32 v222, v222
	s_nop 0
	v_max_f32_e32 v33, 0, v222
	v_exp_f32_e64 v34, -v33
	v_add_f32_e32 v212, v212, v33
	v_xor_b32_e32 v32, 0x80000000, v212
	v_sub_f32_e32 v137, v137, v33
	v_pk_mul_f32 v[14:15], v[14:15], v[34:35] op_sel_hi:[1,0]
	v_pk_mul_f32 v[12:13], v[12:13], v[34:35] op_sel_hi:[1,0]
	v_pk_mul_f32 v[10:11], v[10:11], v[34:35] op_sel_hi:[1,0]
	v_pk_mul_f32 v[8:9], v[8:9], v[34:35] op_sel_hi:[1,0]
	v_pk_mul_f32 v[6:7], v[6:7], v[34:35] op_sel_hi:[1,0]
	v_pk_mul_f32 v[4:5], v[4:5], v[34:35] op_sel_hi:[1,0]
	v_pk_mul_f32 v[2:3], v[2:3], v[34:35] op_sel_hi:[1,0]
	v_pk_mul_f32 v[0:1], v[0:1], v[34:35] op_sel_hi:[1,0]
	v_pk_mul_f32 v[30:31], v[30:31], v[34:35] op_sel_hi:[1,0]
	v_pk_mul_f32 v[28:29], v[28:29], v[34:35] op_sel_hi:[1,0]
	v_pk_mul_f32 v[26:27], v[26:27], v[34:35] op_sel_hi:[1,0]
	v_pk_mul_f32 v[24:25], v[24:25], v[34:35] op_sel_hi:[1,0]
	v_pk_mul_f32 v[22:23], v[22:23], v[34:35] op_sel_hi:[1,0]
	v_pk_mul_f32 v[20:21], v[20:21], v[34:35] op_sel_hi:[1,0]
	v_pk_mul_f32 v[18:19], v[18:19], v[34:35] op_sel_hi:[1,0]
	v_pk_mul_f32 v[16:17], v[16:17], v[34:35] op_sel_hi:[1,0]
	v_sub_f32_e32 v136, v136, v33
	v_sub_f32_e32 v135, v135, v33
	v_sub_f32_e32 v134, v134, v33
	v_sub_f32_e32 v133, v133, v33
	v_sub_f32_e32 v132, v132, v33
	v_sub_f32_e32 v131, v131, v33
	v_sub_f32_e32 v130, v130, v33
	v_sub_f32_e32 v129, v129, v33
	v_sub_f32_e32 v128, v128, v33
	v_sub_f32_e32 v127, v127, v33
	v_sub_f32_e32 v126, v126, v33
	v_sub_f32_e32 v125, v125, v33
	v_sub_f32_e32 v124, v124, v33
	v_sub_f32_e32 v123, v123, v33
	v_sub_f32_e32 v122, v122, v33
	v_sub_f32_e32 v111, v111, v33
	v_sub_f32_e32 v110, v110, v33
	v_sub_f32_e32 v109, v109, v33
	v_sub_f32_e32 v108, v108, v33
	v_sub_f32_e32 v107, v107, v33
	v_sub_f32_e32 v106, v106, v33
	v_sub_f32_e32 v105, v105, v33
	v_sub_f32_e32 v104, v104, v33
	v_sub_f32_e32 v103, v103, v33
	v_sub_f32_e32 v102, v102, v33
	v_sub_f32_e32 v101, v101, v33
	v_sub_f32_e32 v100, v100, v33
	v_sub_f32_e32 v99, v99, v33
	v_sub_f32_e32 v98, v98, v33
	v_sub_f32_e32 v97, v97, v33
	v_sub_f32_e32 v96, v96, v33
	v_mul_f32_e32 v116, v116, v34
	v_mov_b32_e32 v33, v32
	v_mov_b32_e32 v34, v32
	v_mov_b32_e32 v35, v32
	v_mov_b32_e32 v36, v32
	v_mov_b32_e32 v37, v32
	v_mov_b32_e32 v38, v32
	v_mov_b32_e32 v39, v32
	v_mov_b32_e32 v40, v32
	v_mov_b32_e32 v41, v32
	v_mov_b32_e32 v42, v32
	v_mov_b32_e32 v43, v32
	v_mov_b32_e32 v44, v32
	v_mov_b32_e32 v45, v32
	v_mov_b32_e32 v46, v32
	v_mov_b32_e32 v47, v32
	v_mov_b32_e32 v48, v32
	v_mov_b32_e32 v49, v32
	v_mov_b32_e32 v50, v32
	v_mov_b32_e32 v51, v32
	v_mov_b32_e32 v52, v32
	v_mov_b32_e32 v53, v32
	v_mov_b32_e32 v54, v32
	v_mov_b32_e32 v55, v32
	v_mov_b32_e32 v56, v32
	v_mov_b32_e32 v57, v32
	v_mov_b32_e32 v58, v32
	v_mov_b32_e32 v59, v32
	v_mov_b32_e32 v60, v32
	v_mov_b32_e32 v61, v32
	v_mov_b32_e32 v62, v32
	v_mov_b32_e32 v63, v32
	s_branch .LBB0_943

.LBB0_982:
	ds_read_b128 v[118:121], v181 offset:13344
	ds_read_b128 v[122:125], v181 offset:20000
	s_waitcnt lgkmcnt(3)
	v_mfma_f32_32x32x16_bf16 v[128:143], v[96:99], v[144:147], v[32:47]
	v_exp_f32_e32 v117, v80
	v_exp_f32_e32 v126, v81
	v_exp_f32_e32 v127, v82
	v_exp_f32_e32 v213, v83
	v_exp_f32_e32 v214, v84
	v_exp_f32_e32 v215, v85
	s_waitcnt lgkmcnt(2)
	v_mfma_f32_32x32x16_bf16 v[96:111], v[112:115], v[144:147], v[32:47]
	ds_read_b128 v[80:83], v181 offset:13376
	ds_read_b128 v[112:115], v181 offset:20032
	s_waitcnt lgkmcnt(3)
	v_mfma_f32_32x32x16_bf16 v[128:143], v[118:121], v[148:151], v[128:143]
	v_exp_f32_e32 v216, v86
	v_exp_f32_e32 v217, v88
	v_add_f32_e32 v88, v127, v117
	v_add_f32_e32 v86, v213, v126
	s_waitcnt lgkmcnt(2)
	v_mfma_f32_32x32x16_bf16 v[96:111], v[122:125], v[148:151], v[96:111]
	v_cvt_pk_bf16_f32 v84, v117, v126
	v_add_f32_e32 v117, v214, v88
	v_add_f32_e32 v122, v215, v86
	v_exp_f32_e32 v87, v87
	v_exp_f32_e32 v218, v89
	v_exp_f32_e32 v219, v90
	v_exp_f32_e32 v220, v91
	v_cvt_pk_bf16_f32 v85, v127, v213
	v_cvt_pk_bf16_f32 v86, v214, v215
	ds_read_b128 v[88:91], v181 offset:13408
	ds_read_b128 v[118:121], v181 offset:20064
	s_waitcnt lgkmcnt(3)
	v_mfma_f32_32x32x16_bf16 v[128:143], v[80:83], v[152:155], v[128:143]
	v_add_f32_e32 v80, v216, v117
	v_add_f32_e32 v81, v87, v122
	v_add_f32_e32 v82, v217, v80
	v_add_f32_e32 v81, v218, v81
	v_add_f32_e32 v82, v219, v82
	v_add_f32_e32 v83, v220, v81
	s_waitcnt lgkmcnt(2)
	v_mfma_f32_32x32x16_bf16 v[96:111], v[112:115], v[152:155], v[96:111]
	v_exp_f32_e32 v123, v92
	v_exp_f32_e32 v124, v93
	v_exp_f32_e32 v125, v94
	v_exp_f32_e32 v126, v95
	v_cvt_pk_bf16_f32 v87, v216, v87
	v_cvt_pk_bf16_f32 v80, v217, v218
	v_cvt_pk_bf16_f32 v81, v219, v220
	ds_read_b128 v[92:95], v181 offset:13440
	ds_read_b128 v[112:115], v181 offset:20096
	s_waitcnt lgkmcnt(3)
	v_mfma_f32_32x32x16_bf16 v[128:143], v[88:91], v[156:159], v[128:143]
	v_exp_f32_e32 v117, v64
	v_exp_f32_e32 v122, v65
	v_add_f32_e32 v64, v123, v82
	v_add_f32_e32 v65, v124, v83
	v_exp_f32_e32 v214, v68
	v_exp_f32_e32 v215, v69
	s_waitcnt lgkmcnt(2)
	v_mfma_f32_32x32x16_bf16 v[96:111], v[118:121], v[156:159], v[96:111]
	v_add_f32_e32 v68, v125, v64
	v_add_f32_e32 v69, v126, v65
	v_exp_f32_e32 v127, v66
	v_exp_f32_e32 v213, v67
	v_cvt_pk_bf16_f32 v82, v123, v124
	v_cvt_pk_bf16_f32 v83, v125, v126
	ds_read_b128 v[64:67], v181 offset:13472
	ds_read_b128 v[88:91], v181 offset:20128
	s_waitcnt lgkmcnt(3)
	v_mfma_f32_32x32x16_bf16 v[128:143], v[92:95], v[160:163], v[128:143]
	v_exp_f32_e32 v118, v70
	v_add_f32_e32 v70, v117, v68
	v_add_f32_e32 v69, v122, v69
	v_exp_f32_e32 v119, v72
	v_add_f32_e32 v70, v127, v70
	v_add_f32_e32 v72, v213, v69
	s_waitcnt lgkmcnt(2)
	v_mfma_f32_32x32x16_bf16 v[96:111], v[112:115], v[160:163], v[96:111]
	v_add_f32_e32 v112, v214, v70
	v_add_f32_e32 v113, v215, v72
	v_exp_f32_e32 v71, v71
	v_exp_f32_e32 v120, v73
	v_exp_f32_e32 v121, v74
	v_exp_f32_e32 v123, v75
	v_cvt_pk_bf16_f32 v68, v117, v122
	v_cvt_pk_bf16_f32 v69, v127, v213
	v_cvt_pk_bf16_f32 v70, v214, v215
	ds_read_b128 v[72:75], v210 offset:53248
	ds_read_b128 v[92:95], v210 offset:57856
	s_waitcnt lgkmcnt(3)
	v_mfma_f32_32x32x16_bf16 v[128:143], v[64:67], v[164:167], v[128:143]
	v_add_f32_e32 v64, v118, v112
	v_add_f32_e32 v65, v71, v113
	v_add_f32_e32 v66, v119, v64
	v_add_f32_e32 v65, v120, v65
	v_add_f32_e32 v66, v121, v66
	v_add_f32_e32 v67, v123, v65
	s_waitcnt lgkmcnt(2)
	v_mfma_f32_32x32x16_bf16 v[96:111], v[88:91], v[164:167], v[96:111]
	v_exp_f32_e32 v114, v76
	v_exp_f32_e32 v115, v77
	v_exp_f32_e32 v117, v78
	v_exp_f32_e32 v122, v79
	v_cvt_pk_bf16_f32 v71, v118, v71
	v_cvt_pk_bf16_f32 v64, v119, v120
	v_cvt_pk_bf16_f32 v65, v121, v123
	ds_read_b128 v[76:79], v210 offset:53280
	ds_read_b128 v[88:91], v210 offset:57888
	s_waitcnt lgkmcnt(3)
	v_mfma_f32_32x32x16_bf16 v[0:15], v[72:75], v[84:87], v[0:15]
	v_add_f32_e32 v72, v114, v66
	v_add_f32_e32 v67, v115, v67
	v_add_f32_e32 v112, v117, v72
	v_add_f32_e32 v113, v122, v67
	v_cvt_pk_bf16_f32 v66, v114, v115
	v_cvt_pk_bf16_f32 v67, v117, v122
	s_waitcnt lgkmcnt(2)
	v_mfma_f32_32x32x16_bf16 v[16:31], v[92:95], v[84:87], v[16:31]
	ds_read_b128 v[72:75], v210 offset:53312
	s_waitcnt lgkmcnt(2)
	v_mfma_f32_32x32x16_bf16 v[0:15], v[76:79], v[80:83], v[0:15]
	ds_read_b128 v[76:79], v210 offset:57920
	s_waitcnt lgkmcnt(2)
	v_mfma_f32_32x32x16_bf16 v[16:31], v[88:91], v[80:83], v[16:31]
	ds_read_b128 v[80:83], v210 offset:53344
	ds_read_b128 v[88:91], v210 offset:57952
	s_waitcnt lgkmcnt(3)
	v_mfma_f32_32x32x16_bf16 v[0:15], v[72:75], v[68:71], v[0:15]
	s_waitcnt lgkmcnt(2)
	v_mfma_f32_32x32x16_bf16 v[16:31], v[76:79], v[68:71], v[16:31]
	s_waitcnt lgkmcnt(1)
	v_mfma_f32_32x32x16_bf16 v[0:15], v[80:83], v[64:67], v[0:15]
	v_add_f32_e32 v221, v112, v113
	v_cmp_lt_f32_e32 vcc, s59, v221
	v_add_f32_e32 v86, v116, v221
	s_waitcnt lgkmcnt(0)
	v_mfma_f32_32x32x16_bf16 v[16:31], v[88:91], v[64:67], v[16:31]
	ds_read_b128 v[64:67], v181 offset:26624
	ds_read_b128 v[80:83], v181 offset:33280
	s_cbranch_vccnz .Lmla_rare_b_1

.LBB0_988:
	ds_read_b128 v[88:91], v181 offset:26656
	ds_read_b128 v[92:95], v181 offset:33312
	s_waitcnt lgkmcnt(3)
	v_mfma_f32_32x32x16_bf16 v[112:127], v[64:67], v[144:147], v[32:47]
	v_exp_f32_e32 v87, v128
	v_exp_f32_e32 v213, v129
	v_exp_f32_e32 v214, v130
	v_exp_f32_e32 v215, v131
	v_exp_f32_e32 v132, v132
	v_exp_f32_e32 v133, v133
	s_waitcnt lgkmcnt(2)
	v_mfma_f32_32x32x16_bf16 v[64:79], v[80:83], v[144:147], v[32:47]
	ds_read_b128 v[80:83], v181 offset:26688
	ds_read_b128 v[128:131], v181 offset:33344
	s_waitcnt lgkmcnt(3)
	v_mfma_f32_32x32x16_bf16 v[112:127], v[88:91], v[148:151], v[112:127]
	v_cvt_pk_bf16_f32 v88, v87, v213
	v_add_f32_e32 v87, v214, v87
	v_add_f32_e32 v90, v215, v213
	v_add_f32_e32 v87, v132, v87
	s_waitcnt lgkmcnt(2)
	v_mfma_f32_32x32x16_bf16 v[64:79], v[92:95], v[148:151], v[64:79]
	v_add_f32_e32 v91, v133, v90
	v_exp_f32_e32 v216, v134
	v_exp_f32_e32 v217, v135
	v_exp_f32_e32 v136, v136
	v_exp_f32_e32 v137, v137
	v_exp_f32_e32 v138, v138
	v_exp_f32_e32 v139, v139
	v_cvt_pk_bf16_f32 v89, v214, v215
	v_cvt_pk_bf16_f32 v90, v132, v133
	ds_read_b128 v[92:95], v181 offset:26720
	ds_read_b128 v[132:135], v181 offset:33376
	s_waitcnt lgkmcnt(3)
	v_mfma_f32_32x32x16_bf16 v[112:127], v[80:83], v[152:155], v[112:127]
	v_add_f32_e32 v80, v216, v87
	v_add_f32_e32 v81, v217, v91
	v_add_f32_e32 v82, v136, v80
	v_add_f32_e32 v81, v137, v81
	v_add_f32_e32 v82, v138, v82
	v_add_f32_e32 v83, v139, v81
	s_waitcnt lgkmcnt(2)
	v_mfma_f32_32x32x16_bf16 v[64:79], v[128:131], v[152:155], v[64:79]
	v_exp_f32_e32 v140, v140
	v_exp_f32_e32 v141, v141
	v_exp_f32_e32 v142, v142
	v_exp_f32_e32 v143, v143
	v_cvt_pk_bf16_f32 v91, v216, v217
	v_cvt_pk_bf16_f32 v80, v136, v137
	v_cvt_pk_bf16_f32 v81, v138, v139
	ds_read_b128 v[128:131], v181 offset:26752
	ds_read_b128 v[136:139], v181 offset:33408
	s_waitcnt lgkmcnt(3)
	v_mfma_f32_32x32x16_bf16 v[112:127], v[92:95], v[156:159], v[112:127]
	v_exp_f32_e32 v87, v96
	v_add_f32_e32 v92, v140, v82
	v_add_f32_e32 v83, v141, v83
	v_exp_f32_e32 v216, v100
	v_exp_f32_e32 v217, v101
	v_add_f32_e32 v100, v142, v92
	s_waitcnt lgkmcnt(2)
	v_mfma_f32_32x32x16_bf16 v[64:79], v[132:135], v[156:159], v[64:79]
	v_add_f32_e32 v101, v143, v83
	v_exp_f32_e32 v213, v97
	v_exp_f32_e32 v214, v98
	v_exp_f32_e32 v215, v99
	v_cvt_pk_bf16_f32 v82, v140, v141
	v_cvt_pk_bf16_f32 v83, v142, v143
	ds_read_b128 v[92:95], v181 offset:26784
	ds_read_b128 v[96:99], v181 offset:33440
	s_waitcnt lgkmcnt(3)
	v_mfma_f32_32x32x16_bf16 v[112:127], v[128:131], v[160:163], v[112:127]
	v_exp_f32_e32 v132, v102
	v_add_f32_e32 v102, v87, v100
	v_add_f32_e32 v101, v213, v101
	v_cvt_pk_bf16_f32 v100, v87, v213
	v_add_f32_e32 v87, v214, v102
	v_add_f32_e32 v102, v215, v101
	s_waitcnt lgkmcnt(2)
	v_mfma_f32_32x32x16_bf16 v[64:79], v[136:139], v[160:163], v[64:79]
	v_add_f32_e32 v87, v216, v87
	v_add_f32_e32 v136, v217, v102
	v_exp_f32_e32 v103, v103
	v_exp_f32_e32 v133, v104
	v_exp_f32_e32 v134, v105
	v_exp_f32_e32 v135, v106
	v_exp_f32_e32 v140, v107
	v_cvt_pk_bf16_f32 v101, v214, v215
	v_cvt_pk_bf16_f32 v102, v216, v217
	ds_read_b128 v[104:107], v210 offset:62464
	ds_read_b128 v[128:131], v211 offset:13824
	s_waitcnt lgkmcnt(3)
	v_mfma_f32_32x32x16_bf16 v[112:127], v[92:95], v[164:167], v[112:127]
	v_add_f32_e32 v87, v132, v87
	v_add_f32_e32 v92, v103, v136
	v_add_f32_e32 v87, v133, v87
	v_add_f32_e32 v93, v134, v92
	v_add_f32_e32 v87, v135, v87
	v_add_f32_e32 v94, v140, v93
	s_waitcnt lgkmcnt(2)
	v_mfma_f32_32x32x16_bf16 v[64:79], v[96:99], v[164:167], v[64:79]
	v_exp_f32_e32 v137, v108
	v_exp_f32_e32 v138, v109
	v_exp_f32_e32 v139, v110
	v_exp_f32_e32 v141, v111
	v_cvt_pk_bf16_f32 v103, v132, v103
	v_cvt_pk_bf16_f32 v92, v133, v134
	v_cvt_pk_bf16_f32 v93, v135, v140
	ds_read_b128 v[96:99], v210 offset:62496
	ds_read_b128 v[108:111], v211 offset:13856
	s_waitcnt lgkmcnt(3)
	v_mfma_f32_32x32x16_bf16 v[0:15], v[104:107], v[88:91], v[0:15]
	v_add_f32_e32 v87, v137, v87
	v_add_f32_e32 v95, v138, v94
	v_add_f32_e32 v132, v139, v87
	v_add_f32_e32 v133, v141, v95
	v_cvt_pk_bf16_f32 v94, v137, v138
	v_cvt_pk_bf16_f32 v95, v139, v141
	s_waitcnt lgkmcnt(2)
	v_mfma_f32_32x32x16_bf16 v[16:31], v[128:131], v[88:91], v[16:31]
	ds_read_b128 v[88:91], v210 offset:62528
	s_waitcnt lgkmcnt(2)
	v_mfma_f32_32x32x16_bf16 v[0:15], v[96:99], v[80:83], v[0:15]
	ds_read_b128 v[96:99], v211 offset:13888
	s_waitcnt lgkmcnt(2)
	v_mfma_f32_32x32x16_bf16 v[16:31], v[108:111], v[80:83], v[16:31]
	ds_read_b128 v[80:83], v210 offset:62560
	ds_read_b128 v[104:107], v211 offset:13920
	s_waitcnt lgkmcnt(3)
	v_mfma_f32_32x32x16_bf16 v[0:15], v[88:91], v[100:103], v[0:15]
	s_waitcnt lgkmcnt(2)
	v_mfma_f32_32x32x16_bf16 v[16:31], v[96:99], v[100:103], v[16:31]
	s_waitcnt lgkmcnt(1)
	v_mfma_f32_32x32x16_bf16 v[0:15], v[80:83], v[92:95], v[0:15]
	v_add_f32_e32 v221, v132, v133
	v_cmp_lt_f32_e32 vcc, s59, v221
	v_add_f32_e32 v102, v86, v221
	s_waitcnt lgkmcnt(0)
	v_mfma_f32_32x32x16_bf16 v[16:31], v[104:107], v[92:95], v[16:31]
	s_waitcnt vmcnt(0)
	s_barrier
	ds_read_b128 v[80:83], v181 offset:39936
	ds_read_b128 v[96:99], v181 offset:46592
	s_cbranch_vccnz .Lmla_rare_b_2

.LBB0_994:
	ds_read_b128 v[104:107], v181 offset:39968
	ds_read_b128 v[108:111], v181 offset:46624
	s_waitcnt lgkmcnt(3)
	v_mfma_f32_32x32x16_bf16 v[128:143], v[80:83], v[144:147], v[32:47]
	v_exp_f32_e32 v103, v112
	v_exp_f32_e32 v213, v113
	v_exp_f32_e32 v214, v114
	v_exp_f32_e32 v215, v115
	v_exp_f32_e32 v116, v116
	v_exp_f32_e32 v117, v117
	s_waitcnt lgkmcnt(2)
	v_mfma_f32_32x32x16_bf16 v[80:95], v[96:99], v[144:147], v[32:47]
	ds_read_b128 v[96:99], v181 offset:40000
	ds_read_b128 v[112:115], v181 offset:46656
	s_waitcnt lgkmcnt(3)
	v_mfma_f32_32x32x16_bf16 v[128:143], v[104:107], v[148:151], v[128:143]
	v_cvt_pk_bf16_f32 v104, v103, v213
	v_add_f32_e32 v103, v214, v103
	v_add_f32_e32 v106, v215, v213
	v_add_f32_e32 v103, v116, v103
	s_waitcnt lgkmcnt(2)
	v_mfma_f32_32x32x16_bf16 v[80:95], v[108:111], v[148:151], v[80:95]
	v_add_f32_e32 v107, v117, v106
	v_exp_f32_e32 v216, v118
	v_exp_f32_e32 v217, v119
	v_exp_f32_e32 v120, v120
	v_exp_f32_e32 v121, v121
	v_exp_f32_e32 v122, v122
	v_exp_f32_e32 v123, v123
	v_cvt_pk_bf16_f32 v105, v214, v215
	v_cvt_pk_bf16_f32 v106, v116, v117
	ds_read_b128 v[108:111], v181 offset:40032
	ds_read_b128 v[116:119], v181 offset:46688
	s_waitcnt lgkmcnt(3)
	v_mfma_f32_32x32x16_bf16 v[128:143], v[96:99], v[152:155], v[128:143]
	v_add_f32_e32 v96, v216, v103
	v_add_f32_e32 v97, v217, v107
	v_add_f32_e32 v98, v120, v96
	v_add_f32_e32 v97, v121, v97
	v_add_f32_e32 v98, v122, v98
	v_add_f32_e32 v99, v123, v97
	s_waitcnt lgkmcnt(2)
	v_mfma_f32_32x32x16_bf16 v[80:95], v[112:115], v[152:155], v[80:95]
	v_exp_f32_e32 v124, v124
	v_exp_f32_e32 v125, v125
	v_exp_f32_e32 v126, v126
	v_exp_f32_e32 v127, v127
	v_cvt_pk_bf16_f32 v107, v216, v217
	v_cvt_pk_bf16_f32 v96, v120, v121
	v_cvt_pk_bf16_f32 v97, v122, v123
	ds_read_b128 v[112:115], v181 offset:40064
	ds_read_b128 v[120:123], v181 offset:46720
	s_waitcnt lgkmcnt(3)
	v_mfma_f32_32x32x16_bf16 v[128:143], v[108:111], v[156:159], v[128:143]
	v_exp_f32_e32 v103, v64
	v_exp_f32_e32 v213, v65
	v_add_f32_e32 v64, v124, v98
	v_add_f32_e32 v65, v125, v99
	v_exp_f32_e32 v216, v68
	v_exp_f32_e32 v217, v69
	s_waitcnt lgkmcnt(2)
	v_mfma_f32_32x32x16_bf16 v[80:95], v[116:119], v[156:159], v[80:95]
	v_add_f32_e32 v68, v126, v64
	v_add_f32_e32 v69, v127, v65
	v_exp_f32_e32 v214, v66
	v_exp_f32_e32 v215, v67
	v_cvt_pk_bf16_f32 v98, v124, v125
	v_cvt_pk_bf16_f32 v99, v126, v127
	ds_read_b128 v[64:67], v181 offset:40096
	ds_read_b128 v[108:111], v181 offset:46752
	s_waitcnt lgkmcnt(3)
	v_mfma_f32_32x32x16_bf16 v[128:143], v[112:115], v[160:163], v[128:143]
	v_exp_f32_e32 v118, v73
	v_exp_f32_e32 v116, v70
	v_add_f32_e32 v70, v103, v68
	v_add_f32_e32 v69, v213, v69
	v_exp_f32_e32 v117, v72
	v_add_f32_e32 v70, v214, v70
	s_waitcnt lgkmcnt(2)
	v_mfma_f32_32x32x16_bf16 v[80:95], v[120:123], v[160:163], v[80:95]
	v_add_f32_e32 v72, v215, v69
	v_cvt_pk_bf16_f32 v68, v103, v213
	v_add_f32_e32 v103, v216, v70
	v_add_f32_e32 v120, v217, v72
	v_exp_f32_e32 v71, v71
	v_exp_f32_e32 v119, v74
	v_exp_f32_e32 v124, v75
	v_cvt_pk_bf16_f32 v69, v214, v215
	v_cvt_pk_bf16_f32 v70, v216, v217
	ds_read_b128 v[72:75], v211 offset:18432
	ds_read_b128 v[112:115], v211 offset:23040
	s_waitcnt lgkmcnt(3)
	v_mfma_f32_32x32x16_bf16 v[128:143], v[64:67], v[164:167], v[128:143]
	v_add_f32_e32 v64, v116, v103
	v_add_f32_e32 v65, v71, v120
	v_add_f32_e32 v66, v117, v64
	v_add_f32_e32 v65, v118, v65
	v_add_f32_e32 v66, v119, v66
	v_add_f32_e32 v67, v124, v65
	s_waitcnt lgkmcnt(2)
	v_mfma_f32_32x32x16_bf16 v[80:95], v[108:111], v[164:167], v[80:95]
	v_exp_f32_e32 v121, v76
	v_exp_f32_e32 v122, v77
	v_exp_f32_e32 v123, v78
	v_exp_f32_e32 v125, v79
	v_cvt_pk_bf16_f32 v71, v116, v71
	v_cvt_pk_bf16_f32 v64, v117, v118
	v_cvt_pk_bf16_f32 v65, v119, v124
	ds_read_b128 v[76:79], v211 offset:18464
	ds_read_b128 v[108:111], v211 offset:23072
	s_waitcnt lgkmcnt(3)
	v_mfma_f32_32x32x16_bf16 v[0:15], v[72:75], v[104:107], v[0:15]
	v_add_f32_e32 v72, v121, v66
	v_add_f32_e32 v67, v122, v67
	v_add_f32_e32 v103, v123, v72
	v_add_f32_e32 v116, v125, v67
	v_cvt_pk_bf16_f32 v66, v121, v122
	v_cvt_pk_bf16_f32 v67, v123, v125
	s_waitcnt lgkmcnt(2)
	v_mfma_f32_32x32x16_bf16 v[16:31], v[112:115], v[104:107], v[16:31]
	ds_read_b128 v[72:75], v211 offset:18496
	s_waitcnt lgkmcnt(2)
	v_mfma_f32_32x32x16_bf16 v[0:15], v[76:79], v[96:99], v[0:15]
	ds_read_b128 v[76:79], v211 offset:23104
	s_waitcnt lgkmcnt(2)
	v_mfma_f32_32x32x16_bf16 v[16:31], v[108:111], v[96:99], v[16:31]
	ds_read_b128 v[96:99], v211 offset:18528
	ds_read_b128 v[104:107], v211 offset:23136
	s_waitcnt lgkmcnt(3)
	v_mfma_f32_32x32x16_bf16 v[0:15], v[72:75], v[68:71], v[0:15]
	s_waitcnt lgkmcnt(2)
	v_mfma_f32_32x32x16_bf16 v[16:31], v[76:79], v[68:71], v[16:31]
	s_waitcnt lgkmcnt(1)
	v_mfma_f32_32x32x16_bf16 v[0:15], v[96:99], v[64:67], v[0:15]
	v_add_f32_e32 v221, v103, v116
	v_cmp_lt_f32_e32 vcc, s59, v221
	v_add_f32_e32 v118, v102, v221
	s_waitcnt lgkmcnt(0)
	v_mfma_f32_32x32x16_bf16 v[16:31], v[104:107], v[64:67], v[16:31]
	ds_read_b128 v[64:67], v181
	ds_read_b128 v[112:115], v181 offset:6656
	s_cbranch_vccnz .Lmla_rare_b_3

.LBB0_1000:
	ds_read_b128 v[120:123], v181 offset:32
	ds_read_b128 v[124:127], v181 offset:6688
	s_waitcnt lgkmcnt(3)
	v_mfma_f32_32x32x16_bf16 v[96:111], v[64:67], v[144:147], v[32:47]
	v_exp_f32_e32 v119, v128
	v_exp_f32_e32 v213, v129
	v_exp_f32_e32 v214, v130
	v_exp_f32_e32 v215, v131
	v_exp_f32_e32 v132, v132
	v_exp_f32_e32 v133, v133
	s_waitcnt lgkmcnt(2)
	v_mfma_f32_32x32x16_bf16 v[64:79], v[112:115], v[144:147], v[32:47]
	ds_read_b128 v[112:115], v181 offset:64
	ds_read_b128 v[128:131], v181 offset:6720
	s_waitcnt lgkmcnt(3)
	v_mfma_f32_32x32x16_bf16 v[96:111], v[120:123], v[148:151], v[96:111]
	v_cvt_pk_bf16_f32 v120, v119, v213
	v_add_f32_e32 v119, v214, v119
	v_add_f32_e32 v122, v215, v213
	v_add_f32_e32 v119, v132, v119
	s_waitcnt lgkmcnt(2)
	v_mfma_f32_32x32x16_bf16 v[64:79], v[124:127], v[148:151], v[64:79]
	v_add_f32_e32 v123, v133, v122
	v_exp_f32_e32 v216, v134
	v_exp_f32_e32 v217, v135
	v_exp_f32_e32 v136, v136
	v_exp_f32_e32 v137, v137
	v_exp_f32_e32 v138, v138
	v_exp_f32_e32 v139, v139
	v_cvt_pk_bf16_f32 v121, v214, v215
	v_cvt_pk_bf16_f32 v122, v132, v133
	ds_read_b128 v[124:127], v181 offset:96
	ds_read_b128 v[132:135], v181 offset:6752
	s_waitcnt lgkmcnt(3)
	v_mfma_f32_32x32x16_bf16 v[96:111], v[112:115], v[152:155], v[96:111]
	v_add_f32_e32 v112, v216, v119
	v_add_f32_e32 v113, v217, v123
	v_add_f32_e32 v114, v136, v112
	v_add_f32_e32 v113, v137, v113
	v_add_f32_e32 v114, v138, v114
	v_add_f32_e32 v115, v139, v113
	s_waitcnt lgkmcnt(2)
	v_mfma_f32_32x32x16_bf16 v[64:79], v[128:131], v[152:155], v[64:79]
	v_exp_f32_e32 v140, v140
	v_exp_f32_e32 v141, v141
	v_exp_f32_e32 v142, v142
	v_exp_f32_e32 v143, v143
	v_cvt_pk_bf16_f32 v123, v216, v217
	v_cvt_pk_bf16_f32 v112, v136, v137
	v_cvt_pk_bf16_f32 v113, v138, v139
	ds_read_b128 v[128:131], v181 offset:128
	ds_read_b128 v[136:139], v181 offset:6784
	s_waitcnt lgkmcnt(3)
	v_mfma_f32_32x32x16_bf16 v[96:111], v[124:127], v[156:159], v[96:111]
	v_exp_f32_e32 v119, v80
	v_exp_f32_e32 v213, v81
	v_add_f32_e32 v80, v140, v114
	v_add_f32_e32 v81, v141, v115
	v_exp_f32_e32 v216, v84
	v_exp_f32_e32 v217, v85
	s_waitcnt lgkmcnt(2)
	v_mfma_f32_32x32x16_bf16 v[64:79], v[132:135], v[156:159], v[64:79]
	v_add_f32_e32 v84, v142, v80
	v_add_f32_e32 v85, v143, v81
	v_exp_f32_e32 v214, v82
	v_exp_f32_e32 v215, v83
	v_cvt_pk_bf16_f32 v114, v140, v141
	v_cvt_pk_bf16_f32 v115, v142, v143
	ds_read_b128 v[80:83], v181 offset:160
	ds_read_b128 v[124:127], v181 offset:6816
	s_waitcnt lgkmcnt(3)
	v_mfma_f32_32x32x16_bf16 v[96:111], v[128:131], v[160:163], v[96:111]
	v_exp_f32_e32 v132, v86
	v_add_f32_e32 v86, v119, v84
	v_add_f32_e32 v85, v213, v85
	v_exp_f32_e32 v133, v88
	v_add_f32_e32 v86, v214, v86
	v_add_f32_e32 v88, v215, v85
	s_waitcnt lgkmcnt(2)
	v_mfma_f32_32x32x16_bf16 v[64:79], v[136:139], v[160:163], v[64:79]
	v_cvt_pk_bf16_f32 v84, v119, v213
	v_add_f32_e32 v119, v216, v86
	v_add_f32_e32 v136, v217, v88
	v_exp_f32_e32 v87, v87
	v_exp_f32_e32 v134, v89
	v_exp_f32_e32 v135, v90
	v_exp_f32_e32 v140, v91
	v_cvt_pk_bf16_f32 v85, v214, v215
	v_cvt_pk_bf16_f32 v86, v216, v217
	ds_read_b128 v[88:91], v211 offset:27648
	ds_read_b128 v[128:131], v211 offset:32256
	s_waitcnt lgkmcnt(3)
	v_mfma_f32_32x32x16_bf16 v[96:111], v[80:83], v[164:167], v[96:111]
	v_add_f32_e32 v80, v132, v119
	v_add_f32_e32 v81, v87, v136
	v_add_f32_e32 v82, v133, v80
	v_add_f32_e32 v81, v134, v81
	v_add_f32_e32 v82, v135, v82
	v_add_f32_e32 v83, v140, v81
	s_waitcnt lgkmcnt(2)
	v_mfma_f32_32x32x16_bf16 v[64:79], v[124:127], v[164:167], v[64:79]
	v_exp_f32_e32 v137, v92
	v_exp_f32_e32 v138, v93
	v_exp_f32_e32 v139, v94
	v_exp_f32_e32 v141, v95
	v_cvt_pk_bf16_f32 v87, v132, v87
	v_cvt_pk_bf16_f32 v80, v133, v134
	v_cvt_pk_bf16_f32 v81, v135, v140
	ds_read_b128 v[92:95], v211 offset:27680
	ds_read_b128 v[124:127], v211 offset:32288
	s_waitcnt lgkmcnt(3)
	v_mfma_f32_32x32x16_bf16 v[0:15], v[88:91], v[120:123], v[0:15]
	v_add_f32_e32 v88, v137, v82
	v_add_f32_e32 v83, v138, v83
	v_add_f32_e32 v119, v139, v88
	v_add_f32_e32 v132, v141, v83
	v_cvt_pk_bf16_f32 v82, v137, v138
	v_cvt_pk_bf16_f32 v83, v139, v141
	s_waitcnt lgkmcnt(2)
	v_mfma_f32_32x32x16_bf16 v[16:31], v[128:131], v[120:123], v[16:31]
	ds_read_b128 v[88:91], v211 offset:27712
	s_waitcnt lgkmcnt(2)
	v_mfma_f32_32x32x16_bf16 v[0:15], v[92:95], v[112:115], v[0:15]
	ds_read_b128 v[92:95], v211 offset:32320
	s_waitcnt lgkmcnt(2)
	v_mfma_f32_32x32x16_bf16 v[16:31], v[124:127], v[112:115], v[16:31]
	ds_read_b128 v[112:115], v211 offset:27744
	ds_read_b128 v[120:123], v211 offset:32352
	s_waitcnt lgkmcnt(3)
	v_mfma_f32_32x32x16_bf16 v[0:15], v[88:91], v[84:87], v[0:15]
	s_waitcnt lgkmcnt(2)
	v_mfma_f32_32x32x16_bf16 v[16:31], v[92:95], v[84:87], v[16:31]
	s_waitcnt lgkmcnt(1)
	v_mfma_f32_32x32x16_bf16 v[0:15], v[112:115], v[80:83], v[0:15]
	v_add_f32_e32 v221, v119, v132
	v_cmp_lt_f32_e32 vcc, s59, v221
	v_add_f32_e32 v118, v118, v221
	s_waitcnt lgkmcnt(0)
	v_mfma_f32_32x32x16_bf16 v[16:31], v[120:123], v[80:83], v[16:31]
	s_waitcnt vmcnt(0)
	s_barrier
	ds_read_b128 v[80:83], v181 offset:13312
	ds_read_b128 v[112:115], v181 offset:19968
	s_cbranch_vccnz .Lmla_rare_b_4

.LBB0_1006:
	ds_read_b128 v[138:141], v181 offset:13344
	ds_read_b128 v[214:217], v181 offset:20000
	s_waitcnt lgkmcnt(3)
	v_mfma_f32_32x32x16_bf16 v[122:137], v[80:83], v[144:147], v[32:47]
	v_exp_f32_e32 v116, v96
	v_exp_f32_e32 v117, v97
	v_exp_f32_e32 v119, v98
	v_exp_f32_e32 v120, v99
	v_exp_f32_e32 v121, v100
	v_exp_f32_e32 v142, v101
	s_waitcnt lgkmcnt(2)
	v_mfma_f32_32x32x16_bf16 v[80:95], v[112:115], v[144:147], v[32:47]
	ds_read_b128 v[96:99], v181 offset:13376
	ds_read_b128 v[112:115], v181 offset:20032
	s_waitcnt lgkmcnt(3)
	v_mfma_f32_32x32x16_bf16 v[122:137], v[138:141], v[148:151], v[122:137]
	v_exp_f32_e32 v143, v102
	v_exp_f32_e32 v213, v104
	v_add_f32_e32 v104, v119, v116
	v_add_f32_e32 v102, v120, v117
	s_waitcnt lgkmcnt(2)
	v_mfma_f32_32x32x16_bf16 v[80:95], v[214:217], v[148:151], v[80:95]
	v_cvt_pk_bf16_f32 v100, v116, v117
	v_add_f32_e32 v116, v121, v104
	v_add_f32_e32 v117, v142, v102
	v_exp_f32_e32 v103, v103
	v_exp_f32_e32 v218, v105
	v_exp_f32_e32 v219, v106
	v_exp_f32_e32 v220, v107
	v_cvt_pk_bf16_f32 v101, v119, v120
	v_cvt_pk_bf16_f32 v102, v121, v142
	ds_read_b128 v[104:107], v181 offset:13408
	ds_read_b128 v[138:141], v181 offset:20064
	s_waitcnt lgkmcnt(3)
	v_mfma_f32_32x32x16_bf16 v[122:137], v[96:99], v[152:155], v[122:137]
	v_add_f32_e32 v96, v143, v116
	v_add_f32_e32 v97, v103, v117
	v_add_f32_e32 v98, v213, v96
	v_add_f32_e32 v97, v218, v97
	v_add_f32_e32 v98, v219, v98
	v_add_f32_e32 v99, v220, v97
	s_waitcnt lgkmcnt(2)
	v_mfma_f32_32x32x16_bf16 v[80:95], v[112:115], v[152:155], v[80:95]
	v_exp_f32_e32 v119, v108
	v_exp_f32_e32 v120, v109
	v_exp_f32_e32 v121, v110
	v_exp_f32_e32 v142, v111
	v_cvt_pk_bf16_f32 v103, v143, v103
	v_cvt_pk_bf16_f32 v96, v213, v218
	v_cvt_pk_bf16_f32 v97, v219, v220
	ds_read_b128 v[108:111], v181 offset:13440
	ds_read_b128 v[112:115], v181 offset:20096
	s_waitcnt lgkmcnt(3)
	v_mfma_f32_32x32x16_bf16 v[122:137], v[104:107], v[156:159], v[122:137]
	v_exp_f32_e32 v116, v64
	v_exp_f32_e32 v117, v65
	v_add_f32_e32 v64, v119, v98
	v_add_f32_e32 v65, v120, v99
	v_exp_f32_e32 v214, v68
	v_exp_f32_e32 v215, v69
	s_waitcnt lgkmcnt(2)
	v_mfma_f32_32x32x16_bf16 v[80:95], v[138:141], v[156:159], v[80:95]
	v_add_f32_e32 v68, v121, v64
	v_add_f32_e32 v69, v142, v65
	v_exp_f32_e32 v143, v66
	v_exp_f32_e32 v213, v67
	v_cvt_pk_bf16_f32 v98, v119, v120
	v_cvt_pk_bf16_f32 v99, v121, v142
	ds_read_b128 v[64:67], v181 offset:13472
	ds_read_b128 v[104:107], v181 offset:20128
	s_waitcnt lgkmcnt(3)
	v_mfma_f32_32x32x16_bf16 v[122:137], v[108:111], v[160:163], v[122:137]
	v_exp_f32_e32 v119, v70
	v_add_f32_e32 v70, v116, v68
	v_add_f32_e32 v69, v117, v69
	v_exp_f32_e32 v120, v72
	v_add_f32_e32 v70, v143, v70
	v_add_f32_e32 v72, v213, v69
	s_waitcnt lgkmcnt(2)
	v_mfma_f32_32x32x16_bf16 v[80:95], v[112:115], v[160:163], v[80:95]
	v_add_f32_e32 v112, v214, v70
	v_add_f32_e32 v113, v215, v72
	v_exp_f32_e32 v71, v71
	v_exp_f32_e32 v121, v73
	v_exp_f32_e32 v138, v74
	v_exp_f32_e32 v139, v75
	v_cvt_pk_bf16_f32 v68, v116, v117
	v_cvt_pk_bf16_f32 v69, v143, v213
	v_cvt_pk_bf16_f32 v70, v214, v215
	ds_read_b128 v[72:75], v210 offset:53248
	ds_read_b128 v[108:111], v210 offset:57856
	s_waitcnt lgkmcnt(3)
	v_mfma_f32_32x32x16_bf16 v[122:137], v[64:67], v[164:167], v[122:137]
	v_add_f32_e32 v64, v119, v112
	v_add_f32_e32 v65, v71, v113
	v_add_f32_e32 v66, v120, v64
	v_add_f32_e32 v65, v121, v65
	v_add_f32_e32 v66, v138, v66
	v_add_f32_e32 v67, v139, v65
	s_waitcnt lgkmcnt(2)
	v_mfma_f32_32x32x16_bf16 v[80:95], v[104:107], v[164:167], v[80:95]
	v_exp_f32_e32 v114, v76
	v_exp_f32_e32 v115, v77
	v_exp_f32_e32 v116, v78
	v_exp_f32_e32 v117, v79
	v_cvt_pk_bf16_f32 v71, v119, v71
	v_cvt_pk_bf16_f32 v64, v120, v121
	v_cvt_pk_bf16_f32 v65, v138, v139
	ds_read_b128 v[76:79], v210 offset:53280
	ds_read_b128 v[104:107], v210 offset:57888
	s_waitcnt lgkmcnt(3)
	v_mfma_f32_32x32x16_bf16 v[0:15], v[72:75], v[100:103], v[0:15]
	v_add_f32_e32 v72, v114, v66
	v_add_f32_e32 v67, v115, v67
	v_add_f32_e32 v112, v116, v72
	v_add_f32_e32 v113, v117, v67
	v_cvt_pk_bf16_f32 v66, v114, v115
	v_cvt_pk_bf16_f32 v67, v116, v117
	s_waitcnt lgkmcnt(2)
	v_mfma_f32_32x32x16_bf16 v[16:31], v[108:111], v[100:103], v[16:31]
	ds_read_b128 v[72:75], v210 offset:53312
	s_waitcnt lgkmcnt(2)
	v_mfma_f32_32x32x16_bf16 v[0:15], v[76:79], v[96:99], v[0:15]
	ds_read_b128 v[76:79], v210 offset:57920
	s_waitcnt lgkmcnt(2)
	v_mfma_f32_32x32x16_bf16 v[16:31], v[104:107], v[96:99], v[16:31]
	ds_read_b128 v[96:99], v210 offset:53344
	ds_read_b128 v[102:105], v210 offset:57952
	s_waitcnt lgkmcnt(3)
	v_mfma_f32_32x32x16_bf16 v[0:15], v[72:75], v[68:71], v[0:15]
	s_waitcnt lgkmcnt(2)
	v_mfma_f32_32x32x16_bf16 v[16:31], v[76:79], v[68:71], v[16:31]
	s_waitcnt lgkmcnt(1)
	v_mfma_f32_32x32x16_bf16 v[0:15], v[96:99], v[64:67], v[0:15]
	v_add_f32_e32 v221, v112, v113
	v_cmp_lt_f32_e32 vcc, s59, v221
	v_add_f32_e32 v100, v118, v221
	s_waitcnt lgkmcnt(0)
	v_mfma_f32_32x32x16_bf16 v[16:31], v[102:105], v[64:67], v[16:31]
	ds_read_b128 v[64:67], v181 offset:26624
	ds_read_b128 v[96:99], v181 offset:33280
	s_cbranch_vccnz .Lmla_rare_b_5

.LBB0_1012:
	ds_read_b128 v[102:105], v181 offset:26656
	ds_read_b128 v[138:141], v181 offset:33312
	s_waitcnt lgkmcnt(3)
	v_mfma_f32_32x32x16_bf16 v[106:121], v[64:67], v[144:147], v[32:47]
	v_exp_f32_e32 v101, v122
	v_exp_f32_e32 v142, v123
	v_exp_f32_e32 v143, v124
	v_exp_f32_e32 v202, v125
	v_exp_f32_e32 v126, v126
	v_exp_f32_e32 v127, v127
	s_waitcnt lgkmcnt(2)
	v_mfma_f32_32x32x16_bf16 v[64:79], v[96:99], v[144:147], v[32:47]
	ds_read_b128 v[96:99], v181 offset:26688
	ds_read_b128 v[122:125], v181 offset:33344
	s_waitcnt lgkmcnt(3)
	v_mfma_f32_32x32x16_bf16 v[106:121], v[102:105], v[148:151], v[106:121]
	v_cvt_pk_bf16_f32 v102, v101, v142
	v_add_f32_e32 v101, v143, v101
	v_add_f32_e32 v104, v202, v142
	v_add_f32_e32 v101, v126, v101
	s_waitcnt lgkmcnt(2)
	v_mfma_f32_32x32x16_bf16 v[64:79], v[138:141], v[148:151], v[64:79]
	v_add_f32_e32 v105, v127, v104
	v_exp_f32_e32 v203, v128
	v_exp_f32_e32 v204, v129
	v_exp_f32_e32 v205, v130
	v_exp_f32_e32 v213, v131
	v_exp_f32_e32 v214, v132
	v_exp_f32_e32 v215, v133
	v_cvt_pk_bf16_f32 v103, v143, v202
	v_cvt_pk_bf16_f32 v104, v126, v127
	ds_read_b128 v[126:129], v181 offset:26720
	ds_read_b128 v[130:133], v181 offset:33376
	s_waitcnt lgkmcnt(3)
	v_mfma_f32_32x32x16_bf16 v[106:121], v[96:99], v[152:155], v[106:121]
	v_add_f32_e32 v96, v203, v101
	v_add_f32_e32 v97, v204, v105
	v_add_f32_e32 v98, v205, v96
	v_add_f32_e32 v97, v213, v97
	v_add_f32_e32 v98, v214, v98
	v_add_f32_e32 v99, v215, v97
	s_waitcnt lgkmcnt(2)
	v_mfma_f32_32x32x16_bf16 v[64:79], v[122:125], v[152:155], v[64:79]
	v_exp_f32_e32 v138, v134
	v_exp_f32_e32 v139, v135
	v_exp_f32_e32 v140, v136
	v_exp_f32_e32 v141, v137
	v_cvt_pk_bf16_f32 v105, v203, v204
	v_cvt_pk_bf16_f32 v96, v205, v213
	v_cvt_pk_bf16_f32 v97, v214, v215
	ds_read_b128 v[122:125], v181 offset:26752
	ds_read_b128 v[134:137], v181 offset:33408
	s_waitcnt lgkmcnt(3)
	v_mfma_f32_32x32x16_bf16 v[106:121], v[126:129], v[156:159], v[106:121]
	v_exp_f32_e32 v101, v80
	v_exp_f32_e32 v142, v81
	v_add_f32_e32 v80, v138, v98
	v_add_f32_e32 v81, v139, v99
	v_exp_f32_e32 v203, v84
	v_exp_f32_e32 v204, v85
	s_waitcnt lgkmcnt(2)
	v_mfma_f32_32x32x16_bf16 v[64:79], v[130:133], v[156:159], v[64:79]
	v_add_f32_e32 v84, v140, v80
	v_add_f32_e32 v85, v141, v81
	v_exp_f32_e32 v143, v82
	v_exp_f32_e32 v202, v83
	v_cvt_pk_bf16_f32 v98, v138, v139
	v_cvt_pk_bf16_f32 v99, v140, v141
	ds_read_b128 v[80:83], v181 offset:26784
	ds_read_b128 v[126:129], v181 offset:33440
	s_waitcnt lgkmcnt(3)
	v_mfma_f32_32x32x16_bf16 v[106:121], v[122:125], v[160:163], v[106:121]
	v_exp_f32_e32 v87, v87
	v_exp_f32_e32 v130, v86
	v_add_f32_e32 v86, v101, v84
	v_add_f32_e32 v85, v142, v85
	v_exp_f32_e32 v131, v88
	v_add_f32_e32 v86, v143, v86
	s_waitcnt lgkmcnt(2)
	v_mfma_f32_32x32x16_bf16 v[64:79], v[134:137], v[160:163], v[64:79]
	v_add_f32_e32 v88, v202, v85
	v_cvt_pk_bf16_f32 v84, v101, v142
	v_add_f32_e32 v101, v203, v86
	v_add_f32_e32 v134, v204, v88
	v_exp_f32_e32 v132, v89
	v_exp_f32_e32 v133, v90
	v_exp_f32_e32 v138, v91
	v_cvt_pk_bf16_f32 v85, v143, v202
	v_cvt_pk_bf16_f32 v86, v203, v204
	ds_read_b128 v[88:91], v210 offset:62464
	ds_read_b128 v[122:125], v211 offset:13824
	s_waitcnt lgkmcnt(3)
	v_mfma_f32_32x32x16_bf16 v[106:121], v[80:83], v[164:167], v[106:121]
	v_add_f32_e32 v80, v130, v101
	v_add_f32_e32 v81, v87, v134
	v_add_f32_e32 v82, v131, v80
	v_add_f32_e32 v81, v132, v81
	v_add_f32_e32 v82, v133, v82
	v_add_f32_e32 v83, v138, v81
	s_waitcnt lgkmcnt(2)
	v_mfma_f32_32x32x16_bf16 v[64:79], v[126:129], v[164:167], v[64:79]
	v_exp_f32_e32 v135, v92
	v_exp_f32_e32 v136, v93
	v_exp_f32_e32 v137, v94
	v_exp_f32_e32 v139, v95
	v_cvt_pk_bf16_f32 v87, v130, v87
	v_cvt_pk_bf16_f32 v80, v131, v132
	v_cvt_pk_bf16_f32 v81, v133, v138
	ds_read_b128 v[92:95], v210 offset:62496
	ds_read_b128 v[126:129], v211 offset:13856
	s_waitcnt lgkmcnt(3)
	v_mfma_f32_32x32x16_bf16 v[0:15], v[88:91], v[102:105], v[0:15]
	v_add_f32_e32 v88, v135, v82
	v_add_f32_e32 v83, v136, v83
	v_add_f32_e32 v101, v137, v88
	v_add_f32_e32 v130, v139, v83
	v_cvt_pk_bf16_f32 v82, v135, v136
	v_cvt_pk_bf16_f32 v83, v137, v139
	s_waitcnt lgkmcnt(2)
	v_mfma_f32_32x32x16_bf16 v[16:31], v[122:125], v[102:105], v[16:31]
	ds_read_b128 v[88:91], v210 offset:62528
	s_waitcnt lgkmcnt(2)
	v_mfma_f32_32x32x16_bf16 v[0:15], v[92:95], v[96:99], v[0:15]
	ds_read_b128 v[92:95], v211 offset:13888
	s_waitcnt lgkmcnt(2)
	v_mfma_f32_32x32x16_bf16 v[16:31], v[126:129], v[96:99], v[16:31]
	ds_read_b128 v[96:99], v210 offset:62560
	ds_read_b128 v[102:105], v211 offset:13920
	s_waitcnt lgkmcnt(3)
	v_mfma_f32_32x32x16_bf16 v[0:15], v[88:91], v[84:87], v[0:15]
	s_waitcnt lgkmcnt(2)
	v_mfma_f32_32x32x16_bf16 v[16:31], v[92:95], v[84:87], v[16:31]
	s_waitcnt lgkmcnt(1)
	v_mfma_f32_32x32x16_bf16 v[0:15], v[96:99], v[80:83], v[0:15]
	v_add_f32_e32 v221, v101, v130
	v_cmp_lt_f32_e32 vcc, s59, v221
	v_add_f32_e32 v88, v100, v221
	s_waitcnt lgkmcnt(0)
	v_mfma_f32_32x32x16_bf16 v[16:31], v[102:105], v[80:83], v[16:31]
	s_waitcnt vmcnt(0)
	s_barrier
	ds_read_b128 v[84:87], v181 offset:39936
	ds_read_b128 v[80:83], v181 offset:46592
	s_cbranch_vccnz .Lmla_rare_b_6

.LBB0_1018:
	s_waitcnt lgkmcnt(1)
	v_mfma_f32_32x32x16_bf16 v[122:137], v[84:87], v[144:147], v[32:47]
	v_exp_f32_e32 v89, v106
	v_exp_f32_e32 v94, v107
	v_exp_f32_e32 v95, v108
	v_exp_f32_e32 v142, v109
	v_exp_f32_e32 v143, v110
	v_exp_f32_e32 v202, v111
	ds_read_b128 v[84:87], v181 offset:39968
	ds_read_b128 v[90:93], v181 offset:46624
	s_waitcnt lgkmcnt(2)
	v_mfma_f32_32x32x16_bf16 v[96:111], v[80:83], v[144:147], v[32:47]
	ds_read_b128 v[80:83], v181 offset:40000
	ds_read_b128 v[138:141], v181 offset:46656
	s_waitcnt lgkmcnt(3)
	v_mfma_f32_32x32x16_bf16 v[122:137], v[84:87], v[148:151], v[122:137]
	v_exp_f32_e32 v116, v116
	v_add_f32_e32 v87, v95, v89
	v_add_f32_e32 v86, v142, v94
	v_cvt_pk_bf16_f32 v84, v89, v94
	s_waitcnt lgkmcnt(2)
	v_mfma_f32_32x32x16_bf16 v[96:111], v[90:93], v[148:151], v[96:111]
	v_add_f32_e32 v87, v143, v87
	v_add_f32_e32 v89, v202, v86
	v_exp_f32_e32 v203, v112
	v_exp_f32_e32 v204, v113
	v_exp_f32_e32 v205, v114
	v_exp_f32_e32 v213, v115
	v_exp_f32_e32 v117, v117
	v_cvt_pk_bf16_f32 v85, v95, v142
	v_cvt_pk_bf16_f32 v86, v143, v202
	ds_read_b128 v[90:93], v181 offset:40032
	ds_read_b128 v[112:115], v181 offset:46688
	s_waitcnt lgkmcnt(3)
	v_mfma_f32_32x32x16_bf16 v[122:137], v[80:83], v[152:155], v[122:137]
	v_add_f32_e32 v80, v203, v87
	v_add_f32_e32 v81, v204, v89
	v_add_f32_e32 v82, v205, v80
	v_add_f32_e32 v81, v213, v81
	v_add_f32_e32 v82, v116, v82
	v_add_f32_e32 v83, v117, v81
	s_waitcnt lgkmcnt(2)
	v_mfma_f32_32x32x16_bf16 v[96:111], v[138:141], v[152:155], v[96:111]
	v_exp_f32_e32 v94, v118
	v_exp_f32_e32 v95, v119
	v_exp_f32_e32 v120, v120
	v_exp_f32_e32 v121, v121
	v_cvt_pk_bf16_f32 v87, v203, v204
	v_cvt_pk_bf16_f32 v80, v205, v213
	v_cvt_pk_bf16_f32 v81, v116, v117
	ds_read_b128 v[116:119], v181 offset:40064
	ds_read_b128 v[138:141], v181 offset:46720
	s_waitcnt lgkmcnt(3)
	v_mfma_f32_32x32x16_bf16 v[122:137], v[90:93], v[156:159], v[122:137]
	v_exp_f32_e32 v89, v64
	v_exp_f32_e32 v142, v65
	v_add_f32_e32 v64, v94, v82
	v_add_f32_e32 v65, v95, v83
	v_exp_f32_e32 v203, v68
	v_exp_f32_e32 v204, v69
	s_waitcnt lgkmcnt(2)
	v_mfma_f32_32x32x16_bf16 v[96:111], v[112:115], v[156:159], v[96:111]
	v_add_f32_e32 v68, v120, v64
	v_add_f32_e32 v69, v121, v65
	v_exp_f32_e32 v143, v66
	v_exp_f32_e32 v202, v67
	v_cvt_pk_bf16_f32 v82, v94, v95
	v_cvt_pk_bf16_f32 v83, v120, v121
	ds_read_b128 v[64:67], v181 offset:40096
	ds_read_b128 v[90:93], v181 offset:46752
	s_waitcnt lgkmcnt(3)
	v_mfma_f32_32x32x16_bf16 v[122:137], v[116:119], v[160:163], v[122:137]
	v_exp_f32_e32 v116, v74
	v_exp_f32_e32 v94, v70
	v_add_f32_e32 v70, v89, v68
	v_add_f32_e32 v69, v142, v69
	v_exp_f32_e32 v95, v72
	v_add_f32_e32 v70, v143, v70
	s_waitcnt lgkmcnt(2)
	v_mfma_f32_32x32x16_bf16 v[96:111], v[138:141], v[160:163], v[96:111]
	v_add_f32_e32 v72, v202, v69
	v_cvt_pk_bf16_f32 v68, v89, v142
	v_add_f32_e32 v89, v203, v70
	v_add_f32_e32 v118, v204, v72
	v_exp_f32_e32 v71, v71
	v_exp_f32_e32 v120, v73
	v_exp_f32_e32 v117, v75
	v_cvt_pk_bf16_f32 v69, v143, v202
	v_cvt_pk_bf16_f32 v70, v203, v204
	ds_read_b128 v[72:75], v211 offset:18432
	ds_read_b128 v[112:115], v211 offset:23040
	s_waitcnt lgkmcnt(3)
	v_mfma_f32_32x32x16_bf16 v[122:137], v[64:67], v[164:167], v[122:137]
	v_add_f32_e32 v64, v94, v89
	v_add_f32_e32 v65, v71, v118
	v_add_f32_e32 v66, v95, v64
	v_add_f32_e32 v65, v120, v65
	v_add_f32_e32 v66, v116, v66
	v_add_f32_e32 v67, v117, v65
	s_waitcnt lgkmcnt(2)
	v_mfma_f32_32x32x16_bf16 v[96:111], v[90:93], v[164:167], v[96:111]
	v_exp_f32_e32 v119, v76
	v_exp_f32_e32 v121, v77
	v_exp_f32_e32 v138, v78
	v_exp_f32_e32 v139, v79
	v_cvt_pk_bf16_f32 v71, v94, v71
	v_cvt_pk_bf16_f32 v64, v95, v120
	v_cvt_pk_bf16_f32 v65, v116, v117
	ds_read_b128 v[76:79], v211 offset:18464
	ds_read_b128 v[90:93], v211 offset:23072
	s_waitcnt lgkmcnt(3)
	v_mfma_f32_32x32x16_bf16 v[0:15], v[72:75], v[84:87], v[0:15]
	v_add_f32_e32 v72, v119, v66
	v_add_f32_e32 v67, v121, v67
	v_add_f32_e32 v89, v138, v72
	v_add_f32_e32 v94, v139, v67
	v_cvt_pk_bf16_f32 v66, v119, v121
	v_cvt_pk_bf16_f32 v67, v138, v139
	s_waitcnt lgkmcnt(2)
	v_mfma_f32_32x32x16_bf16 v[16:31], v[112:115], v[84:87], v[16:31]
	ds_read_b128 v[72:75], v211 offset:18496
	s_waitcnt lgkmcnt(2)
	v_mfma_f32_32x32x16_bf16 v[0:15], v[76:79], v[80:83], v[0:15]
	ds_read_b128 v[76:79], v211 offset:23104
	s_waitcnt lgkmcnt(2)
	v_mfma_f32_32x32x16_bf16 v[16:31], v[90:93], v[80:83], v[16:31]
	ds_read_b128 v[80:83], v211 offset:18528
	ds_read_b128 v[84:87], v211 offset:23136
	s_waitcnt lgkmcnt(3)
	v_mfma_f32_32x32x16_bf16 v[0:15], v[72:75], v[68:71], v[0:15]
	s_waitcnt lgkmcnt(2)
	v_mfma_f32_32x32x16_bf16 v[16:31], v[76:79], v[68:71], v[16:31]
	s_waitcnt lgkmcnt(1)
	v_mfma_f32_32x32x16_bf16 v[0:15], v[80:83], v[64:67], v[0:15]
	v_add_f32_e32 v221, v89, v94
	v_cmp_lt_f32_e32 vcc, s59, v221
	v_add_f32_e32 v116, v88, v221
	s_waitcnt lgkmcnt(0)
	v_mfma_f32_32x32x16_bf16 v[16:31], v[84:87], v[64:67], v[16:31]
	ds_read_b128 v[64:67], v181
	ds_read_b128 v[112:115], v181 offset:6656
	s_cbranch_vccnz .Lmla_rare_b_7
